# dnpre: has_prev tap pairs packed behind the existing counted waits instead of vmcnt(0) on the spot; array-0 conv weights prefetched one chunk ahead (no vmcnt(0) drain of the raw prefetch at conv start
# baseline (speedup 1.0000x reference)
; __device__ __forceinline__ int tid_() { int t = threadIdx.x; asm volatile("" : "+v"(t)); return t; }
; __device__ void ph_dnpre(const P& p, float* lds) {
;   const int tid = tid_(), lane = tid & 63, w = tid >> 6, fr = lane & 15, fq = lane >> 4;
;   float* B0 = lds; float* B1 = lds + 64 * LS; float* B2 = lds + 2 * 64 * LS;
;   float* sG = lds + 3 * 64 * LS;
;   float* sBeta = sG + 64;
;   float* sEG = sG + 128;
;   u16* DNW = (u16*)p.out;
;   u16* DNQH = DNW + (size_t)4096 * 4096;
;   u16* DNQK = DNQH + (size_t)4096 * 4096;
;   u16* DNKT = DNQK + (size_t)4096 * 4096;
;   float* Ubuf = (float*)p_Abf;
;   u16 xn[3][19]; u16 arn = 0, brn = 0;
;   auto load_raw = [&](int chunk) __attribute__((always_inline)) {
;     const int n = chunk & 127, h = (chunk >> 7) & 7, b = chunk >> 10;
;     const size_t tok0 = (size_t)b * 8192 + n * 64;
;     const bool has_prev = (n * 64 + w * 16) >= 3;
; #pragma unroll
;     for (int arr = 0; arr < 3; ++arr) {
;       const u16* src = p_proj + 768 + arr * 512 + h * 64 + lane;
; #pragma unroll
;       for (int i = 0; i < 19; ++i) {
;         const long row = (long)tok0 + w * 16 + i - 3;
;         xn[arr][i] = (i >= 3 || has_prev) ? src[row * INW] : (u16)0;
;       }
;     }
;     if (w == 0) {
;       arn = p_proj[(tok0 + lane) * INW + 2816 + h];
;       brn = p_proj[(tok0 + lane) * INW + 2824 + h];
;     }
;   };
;   if ((int)blockIdx.x < 4096) load_raw(blockIdx.x);
.LBB0_158:
	v_and_b32_e32 v0, 15, v3
	v_or_b32_e32 v1, v42, v0
	s_movk_i32 s3, 0xfef4
	s_movk_i32 s2, 0x110
	v_mul_lo_u32 v6, v1, s3
	s_movk_i32 s3, 0x10c
	v_lshlrev_b32_e32 v10, 13, v3
	v_lshlrev_b32_e32 v11, 1, v1
	v_lshrrev_b32_e32 v4, 4, v40
	v_mul_lo_u32 v5, v1, s2
	v_mul_lo_u32 v8, v1, s3
	v_and_b32_e32 v10, 0x2000, v10
	v_and_b32_e32 v11, -4, v11
	s_movk_i32 s3, 0x1100
	v_cmp_gt_u32_e64 s[10:11], 2, v40
	v_readlane_b32 s44, v228, 2
	v_cmp_gt_u32_e64 s[0:1], 64, v3
	v_lshlrev_b32_e32 v60, 2, v40
	v_add_u32_e32 v61, v5, v6
	v_lshlrev_b32_e32 v7, 2, v4
	v_add_u32_e32 v10, v10, v11
	v_ashrrev_i32_e32 v11, 1, v3
	v_and_b32_e32 v46, 1, v3
	v_cmp_eq_u32_e64 s[8:9], 0, v3
	v_mul_lo_u32 v69, v2, s3
	v_writelane_b32 v227, s10, 1
	v_lshlrev_b32_e32 v3, 5, v4
	v_lshlrev_b32_e32 v2, 10, v2
	v_readlane_b32 s48, v228, 6
	v_readlane_b32 s49, v228, 7
	v_add_u32_e32 v9, v61, v8
	v_lshlrev_b32_e32 v58, 2, v11
	v_lshlrev_b32_e32 v91, 2, v0
	v_writelane_b32 v227, s11, 2
	v_cmp_gt_u32_e64 s[10:11], 4, v40
	v_add_u32_e32 v64, v5, v3
	v_mad_u32_u24 v65, v0, s2, v3
	v_or_b32_e32 v3, 1, v7
	v_lshl_or_b32 v0, v40, 3, v2
	v_or_b32_e32 v2, v2, v60
	v_readlane_b32 s50, v228, 8
	v_readlane_b32 s51, v228, 9
	s_mov_b64 s[12:13], s[48:49]
	v_add_u32_e32 v6, v9, v6
	v_add_u32_e32 v47, 0x8800, v58
	v_add_u32_e32 v48, 0x4300, v58
	v_mov_b32_e32 v49, 0x4300
	v_mov_b32_e32 v50, 0x8800
	v_cmp_gt_i32_e32 vcc, 64, v11
	v_cmp_lt_i32_e64 s[4:5], 63, v11
	v_or_b32_e32 v11, v7, v42
	v_writelane_b32 v227, s10, 3
	v_and_b32_e32 v66, 48, v40
	v_or_b32_e32 v68, 50, v7
	v_mul_u32_u24_e32 v72, 0x110, v3
	v_lshlrev_b32_e32 v74, 7, v3
	v_ashrrev_i32_e32 v3, 31, v2
	s_mov_b64 s[14:15], s[50:51]
	v_cndmask_b32_e32 v89, v49, v50, vcc
	v_cndmask_b32_e32 v62, v48, v47, vcc
	v_writelane_b32 v227, s11, 4
	v_cmp_gt_u32_e64 s[10:11], 8, v40
	v_or_b32_e32 v48, 16, v7
	v_or_b32_e32 v49, 17, v7
	v_cmp_ge_i32_e64 s[70:71], v1, v68
	v_lshlrev_b32_e32 v87, 7, v68
	v_add3_u32 v68, v6, v8, v66
	v_mul_lo_u32 v8, v11, s2
	v_lshl_add_u64 v[2:3], v[2:3], 2, s[14:15]
	s_mov_b64 s[2:3], 0x3f40000
	v_writelane_b32 v227, s10, 5
	v_cmp_ge_i32_e64 s[30:31], v1, v48
	v_cmp_ge_i32_e64 s[34:35], v1, v49
	v_lshlrev_b32_e32 v77, 7, v48
	v_lshlrev_b32_e32 v78, 7, v49
	v_lshl_add_u64 v[48:49], v[2:3], 0, s[2:3]
	s_add_u32 s2, s14, 0x8141600
	v_writelane_b32 v227, s11, 6
	s_addc_u32 s3, s15, 0
	v_writelane_b32 v227, s2, 7
	v_cmp_ge_i32_e64 s[22:23], v1, v7
	v_cmp_le_i32_e64 s[24:25], v1, v7
	v_writelane_b32 v227, s3, 8
	s_add_u32 s2, s14, 0x8141610
	v_or_b32_e32 v5, 2, v7
	v_or_b32_e32 v47, 3, v7
	v_or_b32_e32 v50, 18, v7
	v_or_b32_e32 v51, 19, v7
	v_or_b32_e32 v52, 32, v7
	v_or_b32_e32 v53, 33, v7
	v_or_b32_e32 v54, 34, v7
	v_or_b32_e32 v55, 35, v7
	v_or_b32_e32 v56, 48, v7
	v_or_b32_e32 v57, 49, v7
	v_or_b32_e32 v7, 51, v7
	s_addc_u32 s3, s15, 0
	v_cmp_ge_i32_e64 s[26:27], v1, v5
	v_cmp_ge_i32_e64 s[28:29], v1, v47
	v_cmp_ge_i32_e64 s[36:37], v1, v50
	v_cmp_ge_i32_e64 s[38:39], v1, v51
	v_cmp_ge_i32_e64 s[40:41], v1, v52
	v_cmp_ge_i32_e64 s[42:43], v1, v53
	v_cmp_ge_i32_e64 s[54:55], v1, v54
	v_cmp_ge_i32_e64 s[58:59], v1, v55
	v_cmp_ge_i32_e64 s[60:61], v1, v56
	v_cmp_ge_i32_e64 s[68:69], v1, v57
	v_cmp_ge_i32_e64 s[72:73], v1, v7
	v_ashrrev_i32_e32 v1, 31, v0
	v_writelane_b32 v227, s2, 9
	v_lshlrev_b32_e32 v79, 7, v50
	v_lshlrev_b32_e32 v80, 7, v51
	v_writelane_b32 v227, s3, 10
	v_lshl_add_u64 v[50:51], v[0:1], 1, s[12:13]
	s_mov_b64 s[2:3], 0x4000000
	v_lshlrev_b32_e32 v81, 7, v52
	v_lshlrev_b32_e32 v82, 7, v53
	v_readlane_b32 s45, v228, 3
	v_lshl_add_u64 v[52:53], v[50:51], 0, s[2:3]
	s_mov_b64 s[2:3], 0x2000000
	v_lshlrev_b32_e32 v83, 7, v54
	v_lshlrev_b32_e32 v84, 7, v55
	s_add_u32 s75, s14, 0x179c8000
	v_lshl_add_u64 v[54:55], v[50:51], 0, s[2:3]
	s_mov_b64 s[2:3], 0x6000000
	v_readlane_b32 s10, v228, 10
	v_readlane_b32 s44, v228, 0
	v_mov_b32_e32 v45, 0
; __device__ __forceinline__ float bf2f(u16 h) { return __uint_as_float(((unsigned)h) << 16); }
; __device__ void ph_dnpre(const P& p, float* lds) {
;     ...
;   if ((int)blockIdx.x < 4096) load_raw(blockIdx.x);
;   for (int chunk = blockIdx.x; chunk < 4096; chunk += gridDim.x) {
;     const int n = chunk & 127, h = (chunk >> 7) & 7, b = chunk >> 10;
;     const size_t tok0 = (size_t)b * 8192 + n * 64;
;     __syncthreads();
;     {
;       u16 xr[3][19];
; #pragma unroll
;       for (int arr = 0; arr < 3; ++arr)
; #pragma unroll
;         for (int i = 0; i < 19; ++i) xr[arr][i] = xn[arr][i];
;       const float ar_raw = bf2f(arn), br_raw = bf2f(brn);
;       if (chunk + (int)gridDim.x < 4096) load_raw(chunk + gridDim.x);
; #pragma unroll
;       for (int arr = 0; arr < 3; ++arr) {
;         const int ch = arr * 512 + h * 64 + lane;
;         const float w0 = p.conv_w[ch], w1 = p.conv_w[1536 + ch], w2 = p.conv_w[3072 + ch], w3 = p.conv_w[4608 + ch];
	v_add_u32_e32 v67, v9, v66
	v_mul_u32_u24_e32 v9, 0x440, v4
	v_lshlrev_b32_e32 v4, 9, v4
	v_lshlrev_b32_e32 v5, 7, v5
	v_lshlrev_b32_e32 v76, 7, v47
	v_lshlrev_b32_e32 v85, 7, v56
	v_lshlrev_b32_e32 v86, 7, v57
	v_lshlrev_b32_e32 v7, 7, v7
	v_mul_u32_u24_e32 v90, 0x110, v46
	s_addc_u32 s33, s15, 0
	v_lshl_add_u64 v[56:57], v[50:51], 0, s[2:3]
	s_add_i32 s2, s44, s10
	v_mbcnt_lo_u32_b32 v0, -1, 0
	v_sub_u32_e32 v41, 2, v42
	v_ashrrev_i32_e32 v43, 31, v42
	v_lshlrev_b32_e32 v63, 13, v46
	s_mov_b32 s63, 0
	v_cmp_eq_u32_e64 s[6:7], 0, v46
	v_cmp_eq_u32_e64 s[66:67], 0, v40
	v_cmp_gt_u32_e64 s[18:19], 16, v40
	v_cmp_gt_u32_e64 s[20:21], 32, v40
	v_lshl_add_u64 v[46:47], s[14:15], 0, v[44:45]
	s_lshl_b32 s12, s2, 6
	s_lshl_b32 s13, s10, 6
	s_movk_i32 s14, 0x1620
	s_mov_b32 s15, 0x5040100
	s_mov_b32 s16, 0x800000
	v_add_u32_e32 v69, v60, v69
	v_mov_b32_e32 v70, 0x3ecc95a3
	v_add_u32_e32 v71, v6, v9
	v_add_u32_e32 v72, v6, v72
	v_add_u32_e32 v73, v10, v4
	v_add_u32_e32 v74, v10, v74
	v_add_u32_e32 v75, v10, v5
	v_add_u32_e32 v76, v10, v76
	v_add_u32_e32 v77, v10, v77
	v_add_u32_e32 v78, v10, v78
	v_add_u32_e32 v79, v10, v79
	v_add_u32_e32 v80, v10, v80
	v_add_u32_e32 v81, v10, v81
	v_add_u32_e32 v82, v10, v82
	v_add_u32_e32 v83, v10, v83
	v_add_u32_e32 v84, v10, v84
	v_add_u32_e32 v85, v10, v85
	v_add_u32_e32 v86, v10, v86
	v_add_u32_e32 v87, v10, v87
	v_add_u32_e32 v88, v10, v7
	v_add_u32_e32 v89, v58, v89
	v_add_u32_e32 v90, v62, v90
	v_add_u32_e32 v91, v91, v8
	v_mov_b32_e32 v58, 0x3f317218
	v_mov_b32_e32 v92, 0x7f800000
	v_mov_b32_e32 v93, 0x7fc00000
	v_mov_b32_e32 v94, 0xff800000
	v_mbcnt_hi_u32_b32 v95, -1, v0
	s_mov_b32 s2, s44
	v_mov_b32_e32 v111, v157
	v_mov_b32_e32 v149, v159
	v_mov_b32_e32 v96, v175
	v_mov_b32_e32 v150, v176
	v_mov_b32_e32 v148, v12
	v_mov_b32_e32 v147, v13
	v_mov_b32_e32 v146, v14
	v_mov_b32_e32 v145, v15
	v_mov_b32_e32 v144, v16
	v_mov_b32_e32 v143, v17
	v_mov_b32_e32 v142, v18
	v_mov_b32_e32 v141, v19
	v_mov_b32_e32 v140, v20
	v_mov_b32_e32 v139, v21
	v_mov_b32_e32 v138, v22
	v_mov_b32_e32 v137, v23
	v_mov_b32_e32 v136, v24
	v_mov_b32_e32 v135, v26
	v_mov_b32_e32 v134, v27
	v_mov_b32_e32 v133, v28
	v_mov_b32_e32 v132, v30
	v_mov_b32_e32 v131, v32
	v_mov_b32_e32 v130, v31
	v_mov_b32_e32 v129, v29
	v_mov_b32_e32 v112, v25
	v_mov_b32_e32 v128, v33
	v_mov_b32_e32 v127, v34
	v_mov_b32_e32 v126, v35
	v_mov_b32_e32 v125, v36
	v_mov_b32_e32 v124, v37
	v_mov_b32_e32 v123, v38
	v_mov_b32_e32 v122, v39
	v_mov_b32_e32 v121, v151
	v_mov_b32_e32 v120, v59
	v_mov_b32_e32 v119, v152
	v_mov_b32_e32 v118, v153
	v_mov_b32_e32 v117, v154
	v_mov_b32_e32 v116, v155
	v_mov_b32_e32 v115, v156
	v_mov_b32_e32 v114, v158
	v_mov_b32_e32 v113, v160
	v_mov_b32_e32 v110, v161
	v_mov_b32_e32 v109, v162
	v_mov_b32_e32 v108, v163
	v_mov_b32_e32 v107, v164
	v_mov_b32_e32 v106, v165
	v_mov_b32_e32 v105, v166
	v_mov_b32_e32 v104, v168
	v_mov_b32_e32 v103, v167
	v_mov_b32_e32 v102, v169
	v_mov_b32_e32 v101, v170
	v_mov_b32_e32 v100, v171
	v_mov_b32_e32 v99, v172
	v_mov_b32_e32 v98, v173
	v_mov_b32_e32 v97, v174
	v_readlane_b32 s46, v228, 4
	v_readlane_b32 s47, v228, 5
	v_readlane_b32 s11, v228, 11
	v_readlane_b32 s45, v228, 1
	v_readlane_b32 s10, v228, 37
	v_readlane_b32 s11, v228, 38
	s_bfe_u32 s44, s2, 0x30007
	v_mov_b32_e32 v191, 0
	v_lshl_or_b32 v190, s44, 8, v60
	v_mov_b32_e32 v194, 0x1000
	v_mov_b32_e32 v195, 0
	v_lshl_add_u64 v[192:193], s[10:11], 0, v[190:191]
	global_load_dword v222, v[192:193], off
	v_lshl_add_u64 v[192:193], v[192:193], 0, v[194:195]
	global_load_dword v223, v[192:193], off offset:2048
	v_lshl_add_u64 v[192:193], v[192:193], 0, v[194:195]
	v_lshl_add_u64 v[192:193], v[192:193], 0, v[194:195]
	global_load_dword v224, v[192:193], off
	v_lshl_add_u64 v[192:193], v[192:193], 0, v[194:195]
	global_load_dword v225, v[192:193], off offset:2048
	s_branch .LBB0_160

; __device__ __forceinline__ float bf2f(u16 h) { return __uint_as_float(((unsigned)h) << 16); }
; __device__ void ph_dnpre(const P& p, float* lds) {
;     ...
;   auto load_raw = [&](int chunk) __attribute__((always_inline)) {
;     const int n = chunk & 127, h = (chunk >> 7) & 7, b = chunk >> 10;
;     const size_t tok0 = (size_t)b * 8192 + n * 64;
;     const bool has_prev = (n * 64 + w * 16) >= 3;
; #pragma unroll
;     for (int arr = 0; arr < 3; ++arr) {
;       const u16* src = p_proj + 768 + arr * 512 + h * 64 + lane;
; #pragma unroll
;       for (int i = 0; i < 19; ++i) {
;         const long row = (long)tok0 + w * 16 + i - 3;
;         xn[arr][i] = (i >= 3 || has_prev) ? src[row * INW] : (u16)0;
;     ...
;   for (int chunk = blockIdx.x; chunk < 4096; chunk += gridDim.x) {
;     const int n = chunk & 127, h = (chunk >> 7) & 7, b = chunk >> 10;
;     const size_t tok0 = (size_t)b * 8192 + n * 64;
;     __syncthreads();
;     {
;       u16 xr[3][19];
; #pragma unroll
;       for (int arr = 0; arr < 3; ++arr)
; #pragma unroll
;         for (int i = 0; i < 19; ++i) xr[arr][i] = xn[arr][i];
;       const float ar_raw = bf2f(arn), br_raw = bf2f(brn);
;       if (chunk + (int)gridDim.x < 4096) load_raw(chunk + gridDim.x);
.LBB0_160:
	v_readlane_b32 s10, v228, 10
	s_add_i32 s17, s2, s10
	s_cmpk_gt_i32 s17, 0xfff
	s_cselect_b64 s[64:65], -1, 0
	s_and_b64 vcc, exec, s[64:65]
	s_waitcnt vmcnt(0) lgkmcnt(0)
	s_barrier
	v_readlane_b32 s11, v228, 11
	s_cbranch_vccnz .LBB0_176
	s_ashr_i32 s10, s17, 10
	s_ashr_i32 s11, s10, 31
	s_lshl_b64 s[96:97], s[10:11], 13
	s_and_b32 s10, s12, 0x1fc0
	s_or_b32 s96, s96, s10
	s_bfe_u32 s3, s17, 0x30007
	v_lshl_add_u64 v[2:3], s[96:97], 0, v[42:43]
	v_cmp_gt_i32_e64 s[56:57], s10, v41
	s_lshl_b32 s62, s3, 7
	v_mad_u64_u32 v[4:5], s[10:11], v2, s14, 0
	v_lshl_add_u64 v[0:1], v[46:47], 0, s[62:63]
	v_mad_i32_i24 v5, v3, s14, v5
	v_mov_b32_e32 v2, 0
	v_lshl_add_u64 v[0:1], v[0:1], 0, v[4:5]
	v_mov_b32_e32 v96, 0
	v_mov_b32_e32 v186, 0
	v_mov_b32_e32 v187, 0
	v_mov_b32_e32 v188, 0
	v_mov_b32_e32 v189, 0
	s_and_saveexec_b64 s[10:11], s[56:57]
	s_cbranch_execz .LBB0_163
	v_add_co_u32_e32 v4, vcc, 0x813c000, v0
	s_nop 1
	v_addc_co_u32_e32 v5, vcc, 0, v1, vcc
	global_load_ushort v186, v[4:5], off offset:928
	v_add_co_u32_e32 v4, vcc, 0x813d000, v0
	s_nop 1
	v_addc_co_u32_e32 v5, vcc, 0, v1, vcc
	global_load_ushort v187, v[4:5], off offset:2496


; __device__ void ph_dnpre(const P& p, float* lds) {
;     ...
;     for (int arr = 0; arr < 3; ++arr) {
;       const u16* src = p_proj + 768 + arr * 512 + h * 64 + lane;
; #pragma unroll
;       for (int i = 0; i < 19; ++i) {
;         const long row = (long)tok0 + w * 16 + i - 3;
;         xn[arr][i] = (i >= 3 || has_prev) ? src[row * INW] : (u16)0;
;       }
;     }
.LBB0_165:
	s_or_b64 exec, exec, s[10:11]
	v_add_co_u32_e32 v4, vcc, 0x8140000, v0
	v_mov_b32_e32 v112, 0
	s_nop 0
	v_addc_co_u32_e32 v5, vcc, 0, v1, vcc
	global_load_ushort v3, v[4:5], off offset:1536
	v_add_co_u32_e32 v4, vcc, 0x8141000, v0
	v_mov_b32_e32 v111, 0
	s_nop 0
	v_addc_co_u32_e32 v5, vcc, 0, v1, vcc
	global_load_ushort v97, v[4:5], off offset:3104
	v_add_co_u32_e32 v4, vcc, 0x8143000, v0
	s_nop 1
	v_addc_co_u32_e32 v5, vcc, 0, v1, vcc
	global_load_ushort v98, v[4:5], off offset:576
	v_add_co_u32_e32 v4, vcc, 0x8144000, v0
	s_nop 1
	v_addc_co_u32_e32 v5, vcc, 0, v1, vcc
	global_load_ushort v99, v[4:5], off offset:2144
	v_add_co_u32_e32 v4, vcc, 0x8145000, v0
	s_nop 1
	v_addc_co_u32_e32 v5, vcc, 0, v1, vcc
	global_load_ushort v100, v[4:5], off offset:3712
	v_add_co_u32_e32 v4, vcc, 0x8147000, v0
	s_nop 1
	v_addc_co_u32_e32 v5, vcc, 0, v1, vcc
	global_load_ushort v101, v[4:5], off offset:1184
	v_add_co_u32_e32 v4, vcc, 0x8148000, v0
	s_nop 1
	v_addc_co_u32_e32 v5, vcc, 0, v1, vcc
	global_load_ushort v102, v[4:5], off offset:2752
	v_add_co_u32_e32 v4, vcc, 0x814a000, v0
	s_nop 1
	v_addc_co_u32_e32 v5, vcc, 0, v1, vcc
	global_load_ushort v103, v[4:5], off offset:224
	v_add_co_u32_e32 v4, vcc, 0x814b000, v0
	s_nop 1
	v_addc_co_u32_e32 v5, vcc, 0, v1, vcc
	global_load_ushort v104, v[4:5], off offset:1792
	v_add_co_u32_e32 v4, vcc, 0x814c000, v0
	s_nop 1
	v_addc_co_u32_e32 v5, vcc, 0, v1, vcc
	global_load_ushort v105, v[4:5], off offset:3360
	v_add_co_u32_e32 v4, vcc, 0x814e000, v0
	s_nop 1
	v_addc_co_u32_e32 v5, vcc, 0, v1, vcc
	global_load_ushort v106, v[4:5], off offset:832
	v_add_co_u32_e32 v4, vcc, 0x814f000, v0
	s_nop 1
	v_addc_co_u32_e32 v5, vcc, 0, v1, vcc
	global_load_ushort v107, v[4:5], off offset:2400
	v_add_co_u32_e32 v4, vcc, 0x8150000, v0
	s_nop 1
	v_addc_co_u32_e32 v5, vcc, 0, v1, vcc
	global_load_ushort v108, v[4:5], off offset:3968
	v_add_co_u32_e32 v4, vcc, 0x8152000, v0
	s_nop 1
	v_addc_co_u32_e32 v5, vcc, 0, v1, vcc
	global_load_ushort v109, v[4:5], off offset:1440
	v_add_co_u32_e32 v4, vcc, 0x8153000, v0
	s_nop 1
	v_addc_co_u32_e32 v5, vcc, 0, v1, vcc
	global_load_ushort v110, v[4:5], off offset:3008
	v_add_co_u32_e32 v4, vcc, 0x8155000, v0
	s_nop 1
	v_addc_co_u32_e32 v5, vcc, 0, v1, vcc
	global_load_ushort v113, v[4:5], off offset:480
	s_and_saveexec_b64 s[10:11], s[56:57]
	s_cbranch_execz .LBB0_167
	v_add_co_u32_e32 v4, vcc, 0x813c000, v0
	s_nop 1
	v_addc_co_u32_e32 v5, vcc, 0, v1, vcc
	global_load_ushort v188, v[4:5], off offset:1952
	v_add_co_u32_e32 v4, vcc, 0x813d000, v0
	s_nop 1
	v_addc_co_u32_e32 v5, vcc, 0, v1, vcc
	global_load_ushort v189, v[4:5], off offset:3520


; __device__ __forceinline__ float bf2f(u16 h) { return __uint_as_float(((unsigned)h) << 16); }
; __device__ __forceinline__ float silu(float y) { return y / (1.f + __expf(-y)); }
; __device__ void ph_dnpre(const P& p, float* lds) {
;     ...
;       if (chunk + (int)gridDim.x < 4096) load_raw(chunk + gridDim.x);
; #pragma unroll
;       for (int arr = 0; arr < 3; ++arr) {
;         const int ch = arr * 512 + h * 64 + lane;
;         const float w0 = p.conv_w[ch], w1 = p.conv_w[1536 + ch], w2 = p.conv_w[3072 + ch], w3 = p.conv_w[4608 + ch];
;         float* dst = arr == 0 ? B0 : (arr == 1 ? B1 : B2);
; #pragma unroll
;         for (int i = 0; i < 16; ++i) {
;           float y = silu(w0 * bf2f(xr[arr][i]) + w1 * bf2f(xr[arr][i + 1]) + w2 * bf2f(xr[arr][i + 2]) + w3 * bf2f(xr[arr][i + 3]));
.LBB0_175:
	s_or_b64 exec, exec, s[56:57]
	s_waitcnt vmcnt(47)
	v_perm_b32 v150, v3, v2, s15
	v_perm_b32 v96, v187, v186, s15
	s_waitcnt vmcnt(31)
	v_perm_b32 v149, v5, v4, s15
	v_perm_b32 v111, v189, v188, s15
.LBB0_176:
	s_bfe_u32 s3, s2, 0x30007
	v_readlane_b32 s80, v228, 33
	v_lshl_or_b32 v44, s3, 8, v60
	v_readlane_b32 s84, v228, 37
	v_readlane_b32 s85, v228, 38
	v_and_b32_e32 v179, 0xffff0000, v175
	v_lshlrev_b32_e32 v178, 16, v175
	v_lshl_add_u64 v[4:5], s[84:85], 0, v[44:45]
	v_add_co_u32_e32 v0, vcc, 0x1000, v4
	s_nop 0
	v_mov_b32_e32 v6, v222
	v_addc_co_u32_e32 v1, vcc, 0, v5, vcc
	v_add_co_u32_e32 v8, vcc, 0x3000, v4
	v_mov_b32_e32 v7, v223
	s_nop 0
	v_addc_co_u32_e32 v9, vcc, 0, v5, vcc
	v_add_co_u32_e32 v2, vcc, 0x4000, v4
	v_mov_b32_e32 v10, v224
	s_nop 0
	v_addc_co_u32_e32 v3, vcc, 0, v5, vcc
	v_mov_b32_e32 v11, v225
	v_readlane_b32 s10, v228, 37
	v_readlane_b32 s11, v228, 38
	s_bfe_u32 s44, s17, 0x30007
	v_mov_b32_e32 v191, 0
	v_lshl_or_b32 v190, s44, 8, v60
	v_mov_b32_e32 v194, 0x1000
	v_mov_b32_e32 v195, 0
	v_lshl_add_u64 v[192:193], s[10:11], 0, v[190:191]
	global_load_dword v222, v[192:193], off
	v_lshl_add_u64 v[192:193], v[192:193], 0, v[194:195]
	global_load_dword v223, v[192:193], off offset:2048
	v_lshl_add_u64 v[192:193], v[192:193], 0, v[194:195]
	v_lshl_add_u64 v[192:193], v[192:193], 0, v[194:195]
	global_load_dword v224, v[192:193], off
	v_lshl_add_u64 v[192:193], v[192:193], 0, v[194:195]
	global_load_dword v225, v[192:193], off offset:2048
	v_lshlrev_b32_e32 v182, 16, v176
	v_and_b32_e32 v183, 0xffff0000, v176
	v_lshlrev_b32_e32 v161, 16, v161
	v_lshlrev_b32_e32 v59, 16, v59
	v_lshlrev_b32_e32 v151, 16, v151
	v_readlane_b32 s81, v228, 34
	v_readlane_b32 s82, v228, 35
	v_readlane_b32 s83, v228, 36
	v_readlane_b32 s86, v228, 39
	v_readlane_b32 s87, v228, 40
	v_readlane_b32 s88, v228, 41
	v_readlane_b32 s89, v228, 42
	v_readlane_b32 s90, v228, 43
	v_readlane_b32 s91, v228, 44
	v_readlane_b32 s92, v228, 45
	v_readlane_b32 s93, v228, 46
	v_readlane_b32 s94, v228, 47
	v_readlane_b32 s95, v228, 48
	s_nop 0
	v_pk_mul_f32 v[180:181], v[6:7], v[178:179]
	s_nop 0
	v_add_f32_e32 v175, v180, v181
	s_nop 0
	v_pk_mul_f32 v[176:177], v[10:11], v[182:183]
	s_nop 0
	v_add_f32_e32 v175, v175, v176
	v_add_f32_e32 v175, v175, v177
	v_mul_f32_e32 v176, 0xbfb8aa3b, v175
	v_exp_f32_e32 v176, v176
	s_nop 0
	v_add_f32_e32 v176, 1.0, v176
	v_div_scale_f32 v177, s[10:11], v176, v176, v175
	v_rcp_f32_e32 v180, v177
	s_nop 0
	v_fma_f32 v181, -v177, v180, 1.0
	v_fmac_f32_e32 v180, v181, v180
	v_div_scale_f32 v181, vcc, v175, v176, v175
	v_mul_f32_e32 v184, v181, v180
	v_fma_f32 v185, -v177, v184, v181
	v_fmac_f32_e32 v184, v185, v180
	v_fma_f32 v177, -v177, v184, v181
	v_div_fmas_f32 v177, v177, v180, v184
	v_div_fixup_f32 v186, v177, v176, v175
	v_pk_mov_b32 v[176:177], v[178:179], v[182:183] op_sel:[1,0]
	v_lshlrev_b32_e32 v175, 16, v174
	s_nop 1
	v_pk_mul_f32 v[176:177], v[6:7], v[176:177]
	v_mov_b32_e32 v174, v183
	v_pk_mul_f32 v[178:179], v[10:11], v[174:175]
	v_add_f32_e32 v176, v176, v177
	v_add_f32_e32 v176, v176, v178
	v_add_f32_e32 v176, v176, v179
	v_mul_f32_e32 v177, 0xbfb8aa3b, v176
	v_exp_f32_e32 v177, v177
	s_nop 0
	v_add_f32_e32 v177, 1.0, v177
	v_div_scale_f32 v178, s[10:11], v177, v177, v176
	v_rcp_f32_e32 v179, v178
	s_nop 0
	v_fma_f32 v181, -v178, v179, 1.0
	v_fmac_f32_e32 v179, v181, v179
	v_div_scale_f32 v181, vcc, v176, v177, v176
	v_mul_f32_e32 v184, v181, v179
	v_fma_f32 v185, -v178, v184, v181
	v_fmac_f32_e32 v184, v185, v179
	v_fma_f32 v178, -v178, v184, v181
	v_div_fmas_f32 v178, v178, v179, v184
	v_div_fixup_f32 v187, v178, v177, v176
	v_mov_b32_e32 v179, v175
	s_nop 0
	v_mov_b32_e32 v226, v69
	v_mov_b32_e32 v176, v6
	v_mov_b32_e32 v177, v10
	v_mov_b32_e32 v178, v182
	v_pk_mul_f32 v[176:177], v[176:177], v[178:179]
	v_lshlrev_b32_e32 v180, 16, v173
	v_fma_f32 v173, v7, v183, v176
	v_add_f32_e32 v173, v173, v177
	v_fmac_f32_e32 v173, v11, v180
	v_mul_f32_e32 v176, 0xbfb8aa3b, v173
	v_exp_f32_e32 v176, v176
	s_nop 0
	v_add_f32_e32 v176, 1.0, v176
	v_div_scale_f32 v177, s[10:11], v176, v176, v173
	v_rcp_f32_e32 v178, v177
	s_nop 0
	v_fma_f32 v179, -v177, v178, 1.0
	v_fmac_f32_e32 v178, v179, v178
	v_div_scale_f32 v179, vcc, v173, v176, v173
	v_mul_f32_e32 v181, v179, v178
	v_fma_f32 v182, -v177, v181, v179
	v_fmac_f32_e32 v181, v182, v178
	v_fma_f32 v177, -v177, v181, v179
	v_div_fmas_f32 v177, v177, v178, v181
	v_div_fixup_f32 v188, v177, v176, v173
	v_lshlrev_b32_e32 v177, 16, v172
	v_pk_mul_f32 v[172:173], v[6:7], v[174:175]
	s_nop 0
	s_nop 1
	v_add_f32_e32 v172, v172, v173
	v_fmac_f32_e32 v172, v10, v180
	v_fmac_f32_e32 v172, v11, v177
	v_mul_f32_e32 v173, 0xbfb8aa3b, v172
	v_exp_f32_e32 v173, v173
	s_nop 0
	v_add_f32_e32 v173, 1.0, v173
	v_div_scale_f32 v174, s[10:11], v173, v173, v172
	v_rcp_f32_e32 v178, v174
	s_nop 0
	v_fma_f32 v179, -v174, v178, 1.0
	v_fmac_f32_e32 v178, v179, v178
	v_div_scale_f32 v179, vcc, v172, v173, v172
	v_mul_f32_e32 v181, v179, v178
	v_fma_f32 v182, -v174, v181, v179
	v_fmac_f32_e32 v181, v182, v178
	v_fma_f32 v174, -v174, v181, v179
	v_div_fmas_f32 v174, v174, v178, v181
	v_div_fixup_f32 v189, v174, v173, v172
	v_lshlrev_b32_e32 v174, 16, v171
	v_mul_f32_e32 v171, v7, v180
	v_fmac_f32_e32 v171, v6, v175
	v_fmac_f32_e32 v171, v10, v177
	s_nop 0
	v_fmac_f32_e32 v171, v11, v174
	s_nop 0
	v_mul_f32_e32 v172, 0xbfb8aa3b, v171
	v_exp_f32_e32 v172, v172
	s_nop 0
	v_add_f32_e32 v172, 1.0, v172
	v_div_scale_f32 v173, s[10:11], v172, v172, v171
	v_rcp_f32_e32 v175, v173
	s_nop 0
	v_fma_f32 v176, -v173, v175, 1.0
	v_fmac_f32_e32 v175, v176, v175
	v_div_scale_f32 v176, vcc, v171, v172, v171
; __device__ __forceinline__ float bf2f(u16 h) { return __uint_as_float(((unsigned)h) << 16); }
; __device__ __forceinline__ float silu(float y) { return y / (1.f + __expf(-y)); }
; __device__ void ph_dnpre(const P& p, float* lds) {
;     ...
; #pragma unroll
;         for (int i = 0; i < 16; ++i) {
;           float y = silu(w0 * bf2f(xr[arr][i]) + w1 * bf2f(xr[arr][i + 1]) + w2 * bf2f(xr[arr][i + 2]) + w3 * bf2f(xr[arr][i + 3]));
	v_mul_f32_e32 v178, v176, v175
	v_fma_f32 v179, -v173, v178, v176
	v_fmac_f32_e32 v178, v179, v175
	v_fma_f32 v173, -v173, v178, v176
	v_div_fmas_f32 v173, v173, v175, v178
	v_div_fixup_f32 v190, v173, v172, v171
	v_lshlrev_b32_e32 v173, 16, v170
	v_mul_f32_e32 v170, v7, v177
	v_fmac_f32_e32 v170, v6, v180
	v_fmac_f32_e32 v170, v10, v174
	s_nop 0
	v_fmac_f32_e32 v170, v11, v173
	s_nop 0
	v_mul_f32_e32 v171, 0xbfb8aa3b, v170
	v_exp_f32_e32 v171, v171
	s_nop 0
	v_add_f32_e32 v171, 1.0, v171
	v_div_scale_f32 v175, s[10:11], v171, v171, v170
	v_rcp_f32_e32 v176, v175
	s_nop 0
	v_fma_f32 v178, -v175, v176, 1.0
	v_fmac_f32_e32 v176, v178, v176
	v_div_scale_f32 v178, vcc, v170, v171, v170
	v_mul_f32_e32 v179, v178, v176
	v_fma_f32 v180, -v175, v179, v178
	v_fmac_f32_e32 v179, v180, v176
	v_fma_f32 v175, -v175, v179, v178
	v_div_fmas_f32 v175, v175, v176, v179
	v_div_fixup_f32 v191, v175, v171, v170
	v_add_u32_e32 v175, 0x400, v69
	v_lshlrev_b32_e32 v172, 16, v169
	v_mul_f32_e32 v169, v7, v174
	v_fmac_f32_e32 v169, v6, v177
	v_fmac_f32_e32 v169, v10, v173
	v_fmac_f32_e32 v169, v11, v172
	v_mul_f32_e32 v170, 0xbfb8aa3b, v169
	v_exp_f32_e32 v170, v170
	s_nop 0
	v_add_f32_e32 v170, 1.0, v170
	v_div_scale_f32 v171, s[10:11], v170, v170, v169
	v_rcp_f32_e32 v176, v171
	s_nop 0
	v_fma_f32 v177, -v171, v176, 1.0
	v_fmac_f32_e32 v176, v177, v176
	v_div_scale_f32 v177, vcc, v169, v170, v169
	v_mul_f32_e32 v178, v177, v176
	v_fma_f32 v179, -v171, v178, v177
	v_fmac_f32_e32 v178, v179, v176
	v_fma_f32 v171, -v171, v178, v177
	v_div_fmas_f32 v171, v171, v176, v178
	v_div_fixup_f32 v192, v171, v170, v169
	v_lshlrev_b32_e32 v176, 16, v167
	v_mul_f32_e32 v167, v7, v173
	s_nop 1
	v_fmac_f32_e32 v167, v6, v174
	v_fmac_f32_e32 v167, v10, v172
	s_nop 0
	v_fmac_f32_e32 v167, v11, v176
	s_nop 0
	s_nop 3
	v_mul_f32_e32 v170, 0xbfb8aa3b, v167
	v_exp_f32_e32 v170, v170
	s_nop 0
	v_add_f32_e32 v170, 1.0, v170
	v_div_scale_f32 v171, s[10:11], v170, v170, v167
	v_rcp_f32_e32 v174, v171
	s_nop 0
	v_fma_f32 v177, -v171, v174, 1.0
	v_fmac_f32_e32 v174, v177, v174
	v_div_scale_f32 v177, vcc, v167, v170, v167
	v_mul_f32_e32 v178, v177, v174
	v_fma_f32 v179, -v171, v178, v177
	v_fmac_f32_e32 v178, v179, v174
	v_fma_f32 v171, -v171, v178, v177
	v_div_fmas_f32 v171, v171, v174, v178
	v_div_fixup_f32 v193, v171, v170, v167
	v_mul_f32_e32 v167, v7, v172
	s_nop 3
	v_fmac_f32_e32 v167, v6, v173
	v_lshlrev_b32_e32 v170, 16, v168
	v_fmac_f32_e32 v167, v10, v176
	v_fmac_f32_e32 v167, v11, v170
	v_mul_f32_e32 v168, 0xbfb8aa3b, v167
	v_exp_f32_e32 v168, v168
	s_nop 0
	v_add_f32_e32 v168, 1.0, v168
	v_div_scale_f32 v169, s[10:11], v168, v168, v167
	v_rcp_f32_e32 v171, v169
	s_nop 0
	v_fma_f32 v173, -v169, v171, 1.0
	v_fmac_f32_e32 v171, v173, v171
	v_div_scale_f32 v173, vcc, v167, v168, v167
	v_mul_f32_e32 v174, v173, v171
	v_fma_f32 v175, -v169, v174, v173
	v_fmac_f32_e32 v174, v175, v171
	v_fma_f32 v169, -v169, v174, v173
	v_div_fmas_f32 v169, v169, v171, v174
	v_div_fixup_f32 v194, v169, v168, v167
	v_lshlrev_b32_e32 v169, 16, v166
	v_mul_f32_e32 v166, v7, v176
	v_fmac_f32_e32 v166, v6, v172
	v_fmac_f32_e32 v166, v10, v170
	s_nop 0
	v_fmac_f32_e32 v166, v11, v169
	s_nop 0
	v_mul_f32_e32 v167, 0xbfb8aa3b, v166
	v_exp_f32_e32 v167, v167
	s_nop 0
	v_add_f32_e32 v167, 1.0, v167
	v_div_scale_f32 v171, s[10:11], v167, v167, v166
	v_rcp_f32_e32 v172, v171
	s_nop 0
	v_fma_f32 v173, -v171, v172, 1.0
	v_fmac_f32_e32 v172, v173, v172
	v_div_scale_f32 v173, vcc, v166, v167, v166
	v_mul_f32_e32 v174, v173, v172
	v_fma_f32 v175, -v171, v174, v173
	v_fmac_f32_e32 v174, v175, v172
	v_fma_f32 v171, -v171, v174, v173
	v_div_fmas_f32 v171, v171, v172, v174
	v_div_fixup_f32 v195, v171, v167, v166
	v_add_u32_e32 v171, 0x800, v69
	v_lshlrev_b32_e32 v168, 16, v165
	v_mul_f32_e32 v165, v7, v170
	v_fmac_f32_e32 v165, v6, v176
	v_fmac_f32_e32 v165, v10, v169
	v_fmac_f32_e32 v165, v11, v168
	v_mul_f32_e32 v166, 0xbfb8aa3b, v165
	v_exp_f32_e32 v166, v166
	s_nop 0
	v_add_f32_e32 v166, 1.0, v166
	v_div_scale_f32 v167, s[10:11], v166, v166, v165
	v_rcp_f32_e32 v172, v167
	s_nop 0
	v_fma_f32 v173, -v167, v172, 1.0
	v_fmac_f32_e32 v172, v173, v172
	v_div_scale_f32 v173, vcc, v165, v166, v165
	v_mul_f32_e32 v174, v173, v172
	v_fma_f32 v175, -v167, v174, v173
	v_fmac_f32_e32 v174, v175, v172
	v_fma_f32 v167, -v167, v174, v173
	v_div_fmas_f32 v167, v167, v172, v174
	v_div_fixup_f32 v196, v167, v166, v165
	v_lshlrev_b32_e32 v167, 16, v164
	v_mul_f32_e32 v164, v7, v169
	v_fmac_f32_e32 v164, v6, v170
	v_fmac_f32_e32 v164, v10, v168
	s_nop 0
	v_fmac_f32_e32 v164, v11, v167
	s_nop 0
	v_mul_f32_e32 v165, 0xbfb8aa3b, v164
	v_exp_f32_e32 v165, v165
	s_nop 0
	v_add_f32_e32 v165, 1.0, v165
	v_div_scale_f32 v170, s[10:11], v165, v165, v164
	v_rcp_f32_e32 v172, v170
	s_nop 0
	v_fma_f32 v173, -v170, v172, 1.0
	v_fmac_f32_e32 v172, v173, v172
	v_div_scale_f32 v173, vcc, v164, v165, v164
	v_mul_f32_e32 v174, v173, v172
	v_fma_f32 v175, -v170, v174, v173
	v_fmac_f32_e32 v174, v175, v172
	v_fma_f32 v170, -v170, v174, v173
	v_div_fmas_f32 v170, v170, v172, v174
	v_div_fixup_f32 v197, v170, v165, v164
	v_lshlrev_b32_e32 v166, 16, v163
	v_mul_f32_e32 v163, v7, v168
	v_fmac_f32_e32 v163, v6, v169
	v_fmac_f32_e32 v163, v10, v167
	v_fmac_f32_e32 v163, v11, v166
	v_mul_f32_e32 v164, 0xbfb8aa3b, v163
	v_exp_f32_e32 v164, v164
	s_nop 0
	v_add_f32_e32 v164, 1.0, v164
	v_div_scale_f32 v165, s[10:11], v164, v164, v163
	v_rcp_f32_e32 v169, v165
	s_nop 0
	v_fma_f32 v170, -v165, v169, 1.0
	v_fmac_f32_e32 v169, v170, v169
	v_div_scale_f32 v170, vcc, v163, v164, v163
	v_mul_f32_e32 v171, v170, v169
	v_fma_f32 v172, -v165, v171, v170
	v_fmac_f32_e32 v171, v172, v169
; __device__ __forceinline__ float bf2f(u16 h) { return __uint_as_float(((unsigned)h) << 16); }
; __device__ __forceinline__ float silu(float y) { return y / (1.f + __expf(-y)); }
; __device__ void ph_dnpre(const P& p, float* lds) {
;     ...
;       for (int arr = 0; arr < 3; ++arr) {
;         const int ch = arr * 512 + h * 64 + lane;
;         const float w0 = p.conv_w[ch], w1 = p.conv_w[1536 + ch], w2 = p.conv_w[3072 + ch], w3 = p.conv_w[4608 + ch];
;         float* dst = arr == 0 ? B0 : (arr == 1 ? B1 : B2);
; #pragma unroll
;         for (int i = 0; i < 16; ++i) {
;           float y = silu(w0 * bf2f(xr[arr][i]) + w1 * bf2f(xr[arr][i + 1]) + w2 * bf2f(xr[arr][i + 2]) + w3 * bf2f(xr[arr][i + 3]));
;           if (arr < 2) {
;             float ss = wave_sum(y * y);
;             y *= rsqrtf(ss + EPS) * (arr == 0 ? 0.125f : 1.f);
;           }
;           dst[(w * 16 + i) * LS + lane] = y;
;         }
	v_fma_f32 v165, -v165, v171, v170
	v_div_fmas_f32 v165, v165, v169, v171
	v_div_fixup_f32 v198, v165, v164, v163
	v_lshlrev_b32_e32 v165, 16, v162
	v_mul_f32_e32 v162, v7, v167
	v_fmac_f32_e32 v162, v6, v168
	v_fmac_f32_e32 v162, v10, v166
	s_nop 0
	v_fmac_f32_e32 v162, v11, v165
	s_nop 0
	v_mul_f32_e32 v163, 0xbfb8aa3b, v162
	v_exp_f32_e32 v163, v163
	s_nop 0
	v_add_f32_e32 v163, 1.0, v163
	v_div_scale_f32 v168, s[10:11], v163, v163, v162
	v_rcp_f32_e32 v169, v168
	s_nop 0
	v_fma_f32 v170, -v168, v169, 1.0
	v_fmac_f32_e32 v169, v170, v169
	v_div_scale_f32 v170, vcc, v162, v163, v162
	v_mul_f32_e32 v171, v170, v169
	v_fma_f32 v172, -v168, v171, v170
	v_fmac_f32_e32 v171, v172, v169
	v_fma_f32 v168, -v168, v171, v170
	v_div_fmas_f32 v168, v168, v169, v171
	v_div_fixup_f32 v199, v168, v163, v162
	v_add_u32_e32 v168, 0xc00, v69
	v_mul_f32_e32 v162, v7, v166
	v_fmac_f32_e32 v162, v6, v167
	v_fmac_f32_e32 v162, v10, v165
	v_fmac_f32_e32 v162, v11, v161
	v_mul_f32_e32 v163, 0xbfb8aa3b, v162
	v_exp_f32_e32 v163, v163
	v_mul_f32_e32 v7, v7, v165
	v_fmac_f32_e32 v7, v6, v166
	v_fmac_f32_e32 v7, v10, v161
	v_add_f32_e32 v163, 1.0, v163
	v_div_scale_f32 v164, s[10:11], v163, v163, v162
	v_rcp_f32_e32 v167, v164
	v_lshlrev_b32_e32 v6, 16, v160
	v_fmac_f32_e32 v7, v11, v6
	v_mul_f32_e32 v6, 0xbfb8aa3b, v7
	v_fma_f32 v169, -v164, v167, 1.0
	v_fmac_f32_e32 v167, v169, v167
	v_div_scale_f32 v169, vcc, v162, v163, v162
	v_mul_f32_e32 v170, v169, v167
	v_fma_f32 v171, -v164, v170, v169
	v_fmac_f32_e32 v170, v171, v167
	v_fma_f32 v164, -v164, v170, v169
	v_div_fmas_f32 v164, v164, v167, v170
	v_div_fixup_f32 v200, v164, v163, v162
	v_exp_f32_e32 v6, v6
	v_and_b32_e32 v165, 0xffff0000, v159
	s_nop 1
	v_add_f32_e32 v6, 1.0, v6
	s_nop 0
	s_nop 3
	v_div_scale_f32 v10, s[10:11], v6, v6, v7
	s_nop 3
	v_rcp_f32_e32 v11, v10
	s_nop 1
	v_fma_f32 v160, -v10, v11, 1.0
	v_fmac_f32_e32 v11, v160, v11
	v_div_scale_f32 v160, vcc, v7, v6, v7
	s_nop 1
	v_mul_f32_e32 v161, v160, v11
	v_fma_f32 v163, -v10, v161, v160
	v_fmac_f32_e32 v161, v163, v11
	v_fma_f32 v10, -v10, v161, v160
	v_div_fmas_f32 v10, v10, v11, v161
	v_div_fixup_f32 v201, v10, v6, v7
	v_and_b32_e32 v161, 0xffff0000, v157
	v_lshlrev_b32_e32 v160, 16, v157
	v_lshlrev_b32_e32 v164, 16, v159
	s_nop 0
	s_movk_i32 s10, 0x2000
	v_add_co_u32_e32 v10, vcc, s10, v4
	s_movk_i32 s10, 0x5000
	s_nop 0
	v_addc_co_u32_e32 v11, vcc, 0, v5, vcc
	v_add_co_u32_e32 v4, vcc, s10, v4
	v_mul_f32_e32 v202, v186, v186
	v_mul_f32_e32 v203, v187, v187
	v_mul_f32_e32 v204, v188, v188
	v_mul_f32_e32 v205, v189, v189
	v_mul_f32_e32 v206, v190, v190
	v_mul_f32_e32 v207, v191, v191
	v_mul_f32_e32 v208, v192, v192
	v_mul_f32_e32 v209, v193, v193
	v_mul_f32_e32 v210, v194, v194
	v_mul_f32_e32 v211, v195, v195
	v_mul_f32_e32 v212, v196, v196
	v_mul_f32_e32 v213, v197, v197
	v_mul_f32_e32 v214, v198, v198
	v_mul_f32_e32 v215, v199, v199
	v_mul_f32_e32 v216, v200, v200
	v_mul_f32_e32 v217, v201, v201
	v_permlane32_swap_b32 v202, v210
	v_permlane32_swap_b32 v203, v211
	v_permlane32_swap_b32 v204, v212
	v_permlane32_swap_b32 v205, v213
	v_permlane32_swap_b32 v206, v214
	v_permlane32_swap_b32 v207, v215
	v_permlane32_swap_b32 v208, v216
	v_permlane32_swap_b32 v209, v217
	v_add_f32_e32 v202, v202, v210
	v_add_f32_e32 v203, v203, v211
	v_add_f32_e32 v204, v204, v212
	v_add_f32_e32 v205, v205, v213
	v_add_f32_e32 v206, v206, v214
	v_add_f32_e32 v207, v207, v215
	v_add_f32_e32 v208, v208, v216
	v_add_f32_e32 v209, v209, v217
	v_permlane16_swap_b32 v202, v206
	v_permlane16_swap_b32 v203, v207
	v_permlane16_swap_b32 v204, v208
	v_permlane16_swap_b32 v205, v209
	s_mov_b32 s44, 0xff00ff00
	s_mov_b32 s45, 0xff00ff00
	v_add_f32_e32 v202, v202, v206
	v_add_f32_e32 v203, v203, v207
	v_add_f32_e32 v204, v204, v208
	v_add_f32_e32 v205, v205, v209
	v_add_u32_e32 v214, 0x400, v226
	v_add_u32_e32 v215, 0x800, v226
	v_cndmask_b32_e64 v210, v204, v202, s[44:45]
	v_cndmask_b32_e64 v211, v202, v204, s[44:45]
	v_cndmask_b32_e64 v212, v205, v203, s[44:45]
	v_cndmask_b32_e64 v213, v203, v205, s[44:45]
	v_add_u32_e32 v216, 0xc00, v226
	s_nop 0
	v_add_f32_dpp v202, v210, v211 row_ror:8 row_mask:0xf bank_mask:0xf
	v_add_f32_dpp v203, v212, v213 row_ror:8 row_mask:0xf bank_mask:0xf
	s_nop 0
	v_add_f32_dpp v202, v202, v202 quad_perm:[1,0,3,2] row_mask:0xf bank_mask:0xf
	v_add_f32_dpp v203, v203, v203 quad_perm:[1,0,3,2] row_mask:0xf bank_mask:0xf
	s_nop 0
	v_add_f32_dpp v202, v202, v202 quad_perm:[2,3,0,1] row_mask:0xf bank_mask:0xf
	v_add_f32_dpp v203, v203, v203 quad_perm:[2,3,0,1] row_mask:0xf bank_mask:0xf
	s_nop 0
	v_add_f32_dpp v202, v202, v202 row_half_mirror row_mask:0xf bank_mask:0xf
	v_add_f32_dpp v203, v203, v203 row_half_mirror row_mask:0xf bank_mask:0xf
	v_add_f32_e32 v202, 0x358637bd, v202
	v_add_f32_e32 v203, 0x358637bd, v203
	v_rsq_f32_e32 v202, v202
	v_rsq_f32_e32 v203, v203
	s_nop 0
	v_mul_f32_e32 v202, 0x3e000000, v202
	v_mul_f32_e32 v203, 0x3e000000, v203
	s_nop 0
	v_readlane_b32 s44, v202, 0
	v_readlane_b32 s45, v203, 0
	v_readlane_b32 s10, v202, 8
	v_readlane_b32 s11, v203, 8
	v_mul_f32_e32 v186, s44, v186
	v_mul_f32_e32 v187, s45, v187
	v_mul_f32_e32 v188, s10, v188
	v_mul_f32_e32 v189, s11, v189
	ds_write2_b32 v226, v186, v187 offset1:68
	ds_write2_b32 v226, v188, v189 offset0:136 offset1:204
	v_readlane_b32 s44, v202, 16
	v_readlane_b32 s45, v203, 16
	v_readlane_b32 s10, v202, 24
	v_readlane_b32 s11, v203, 24
	v_mul_f32_e32 v190, s44, v190
	v_mul_f32_e32 v191, s45, v191
	v_mul_f32_e32 v192, s10, v192
	v_mul_f32_e32 v193, s11, v193
	ds_write2_b32 v214, v190, v191 offset0:16 offset1:84
	ds_write2_b32 v214, v192, v193 offset0:152 offset1:220
	v_readlane_b32 s44, v202, 32
	v_readlane_b32 s45, v203, 32
	v_readlane_b32 s10, v202, 40
	v_readlane_b32 s11, v203, 40
	v_mul_f32_e32 v194, s44, v194
	v_mul_f32_e32 v195, s45, v195
	v_mul_f32_e32 v196, s10, v196
	v_mul_f32_e32 v197, s11, v197
	ds_write2_b32 v215, v194, v195 offset0:32 offset1:100
	ds_write2_b32 v215, v196, v197 offset0:168 offset1:236
	v_readlane_b32 s44, v202, 48
	v_readlane_b32 s45, v203, 48
	v_readlane_b32 s10, v202, 56
	v_readlane_b32 s11, v203, 56
	v_mul_f32_e32 v198, s44, v198
	v_mul_f32_e32 v199, s45, v199
	v_mul_f32_e32 v200, s10, v200
	v_mul_f32_e32 v201, s11, v201
	ds_write2_b32 v216, v198, v199 offset0:48 offset1:116
	ds_write2_b32 v216, v200, v201 offset0:184 offset1:252
	global_load_dword v6, v44, s[84:85] offset:2048
	v_addc_co_u32_e32 v5, vcc, 0, v5, vcc
	global_load_dword v7, v[10:11], off
	s_nop 0
	global_load_dword v8, v[8:9], off offset:2048
	s_waitcnt vmcnt(1)
; __device__ __forceinline__ float bf2f(u16 h) { return __uint_as_float(((unsigned)h) << 16); }
; __device__ __forceinline__ float silu(float y) { return y / (1.f + __expf(-y)); }
; __device__ void ph_dnpre(const P& p, float* lds) {
;     ...
;       for (int arr = 0; arr < 3; ++arr) {
;         const int ch = arr * 512 + h * 64 + lane;
;         const float w0 = p.conv_w[ch], w1 = p.conv_w[1536 + ch], w2 = p.conv_w[3072 + ch], w3 = p.conv_w[4608 + ch];
;         float* dst = arr == 0 ? B0 : (arr == 1 ? B1 : B2);
; #pragma unroll
;         for (int i = 0; i < 16; ++i) {
;           float y = silu(w0 * bf2f(xr[arr][i]) + w1 * bf2f(xr[arr][i + 1]) + w2 * bf2f(xr[arr][i + 2]) + w3 * bf2f(xr[arr][i + 3]));
	v_pk_mul_f32 v[162:163], v[6:7], v[160:161]
	global_load_dword v9, v[4:5], off
	v_add_f32_e32 v44, v162, v163
	s_waitcnt vmcnt(0)
	v_pk_mul_f32 v[166:167], v[8:9], v[164:165]
	s_nop 0
	v_add_f32_e32 v44, v44, v166
	v_add_f32_e32 v44, v44, v167
	v_mul_f32_e32 v157, 0xbfb8aa3b, v44
	v_exp_f32_e32 v157, v157
	s_nop 0
	v_add_f32_e32 v157, 1.0, v157
	v_div_scale_f32 v159, s[10:11], v157, v157, v44
	v_rcp_f32_e32 v160, v159
	s_nop 0
	v_fma_f32 v162, -v159, v160, 1.0
	v_fmac_f32_e32 v160, v162, v160
	v_div_scale_f32 v162, vcc, v44, v157, v44
	v_mul_f32_e32 v163, v162, v160
	v_fma_f32 v166, -v159, v163, v162
	v_fmac_f32_e32 v163, v166, v160
	v_fma_f32 v159, -v159, v163, v162
	v_div_fmas_f32 v159, v159, v160, v163
	v_div_fixup_f32 v186, v159, v157, v44
	v_pk_mov_b32 v[160:161], v[160:161], v[164:165] op_sel:[1,0]
	s_nop 0
	s_nop 1
	v_pk_mul_f32 v[160:161], v[6:7], v[160:161]
	s_nop 0
	v_lshlrev_b32_e32 v159, 16, v158
	v_mov_b32_e32 v158, v165
	s_nop 0
	v_pk_mul_f32 v[162:163], v[8:9], v[158:159]
	v_add_f32_e32 v157, v160, v161
	v_add_f32_e32 v157, v157, v162
	v_add_f32_e32 v157, v157, v163
	v_mul_f32_e32 v160, 0xbfb8aa3b, v157
	v_exp_f32_e32 v160, v160
	s_nop 0
	v_add_f32_e32 v160, 1.0, v160
	v_div_scale_f32 v161, s[10:11], v160, v160, v157
	v_rcp_f32_e32 v162, v161
	s_nop 0
	v_fma_f32 v163, -v161, v162, 1.0
	v_fmac_f32_e32 v162, v163, v162
	v_div_scale_f32 v163, vcc, v157, v160, v157
	v_mul_f32_e32 v166, v163, v162
	v_fma_f32 v167, -v161, v166, v163
	v_fmac_f32_e32 v166, v167, v162
	v_fma_f32 v161, -v161, v166, v163
	v_div_fmas_f32 v161, v161, v162, v166
	v_div_fixup_f32 v187, v161, v160, v157
	v_add_u32_e32 v162, 0x4400, v69
	s_nop 0
	v_mov_b32_e32 v226, v162
	v_lshlrev_b32_e32 v44, 16, v156
	v_mov_b32_e32 v156, v6
	v_mov_b32_e32 v157, v8
	v_mov_b32_e32 v160, v164
	v_mov_b32_e32 v161, v159
	v_pk_mul_f32 v[156:157], v[156:157], v[160:161]
	s_nop 0
	v_fma_f32 v156, v7, v165, v156
	v_add_f32_e32 v156, v156, v157
	v_fmac_f32_e32 v156, v9, v44
	v_mul_f32_e32 v157, 0xbfb8aa3b, v156
	v_exp_f32_e32 v157, v157
	s_nop 0
	v_add_f32_e32 v157, 1.0, v157
	v_div_scale_f32 v160, s[10:11], v157, v157, v156
	v_rcp_f32_e32 v161, v160
	s_nop 0
	v_fma_f32 v163, -v160, v161, 1.0
	v_fmac_f32_e32 v161, v163, v161
	v_div_scale_f32 v163, vcc, v156, v157, v156
	v_mul_f32_e32 v164, v163, v161
	v_fma_f32 v165, -v160, v164, v163
	v_fmac_f32_e32 v164, v165, v161
	v_fma_f32 v160, -v160, v164, v163
	v_div_fmas_f32 v160, v160, v161, v164
	v_div_fixup_f32 v188, v160, v157, v156
	v_lshlrev_b32_e32 v161, 16, v155
	s_nop 0
	v_pk_mul_f32 v[156:157], v[6:7], v[158:159]
	s_nop 0
	v_add_f32_e32 v155, v156, v157
	v_fmac_f32_e32 v155, v8, v44
	v_fmac_f32_e32 v155, v9, v161
	v_mul_f32_e32 v156, 0xbfb8aa3b, v155
	v_exp_f32_e32 v156, v156
	s_nop 0
	v_add_f32_e32 v156, 1.0, v156
	v_div_scale_f32 v157, s[10:11], v156, v156, v155
	v_rcp_f32_e32 v158, v157
	s_nop 0
	v_fma_f32 v163, -v157, v158, 1.0
	v_fmac_f32_e32 v158, v163, v158
	v_div_scale_f32 v163, vcc, v155, v156, v155
	v_mul_f32_e32 v164, v163, v158
	v_fma_f32 v165, -v157, v164, v163
	v_fmac_f32_e32 v164, v165, v158
	v_fma_f32 v157, -v157, v164, v163
	v_div_fmas_f32 v157, v157, v158, v164
	v_div_fixup_f32 v189, v157, v156, v155
	v_lshlrev_b32_e32 v156, 16, v154
	v_mul_f32_e32 v154, v7, v44
	v_fmac_f32_e32 v154, v6, v159
	v_fmac_f32_e32 v154, v8, v161
	v_fmac_f32_e32 v154, v9, v156
	s_nop 0
	v_mul_f32_e32 v155, 0xbfb8aa3b, v154
	v_exp_f32_e32 v155, v155
	s_nop 0
	v_add_f32_e32 v155, 1.0, v155
	v_div_scale_f32 v157, s[10:11], v155, v155, v154
	v_rcp_f32_e32 v158, v157
	s_nop 0
	v_fma_f32 v159, -v157, v158, 1.0
	v_fmac_f32_e32 v158, v159, v158
	v_div_scale_f32 v159, vcc, v154, v155, v154
	v_mul_f32_e32 v160, v159, v158
	v_fma_f32 v162, -v157, v160, v159
	v_fmac_f32_e32 v160, v162, v158
	v_fma_f32 v157, -v157, v160, v159
	v_div_fmas_f32 v157, v157, v158, v160
	v_div_fixup_f32 v190, v157, v155, v154
	v_lshlrev_b32_e32 v158, 16, v153
	v_mul_f32_e32 v153, v7, v161
	s_nop 1
	v_fmac_f32_e32 v153, v6, v44
	v_fmac_f32_e32 v153, v8, v156
	s_nop 0
	v_fmac_f32_e32 v153, v9, v158
	v_mul_f32_e32 v44, 0xbfb8aa3b, v153
	s_nop 0
	v_exp_f32_e32 v44, v44
	s_nop 0
	s_nop 0
	v_add_f32_e32 v44, 1.0, v44
	s_nop 4
	v_div_scale_f32 v154, s[10:11], v44, v44, v153
	v_rcp_f32_e32 v155, v154
	s_nop 0
	v_fma_f32 v159, -v154, v155, 1.0
	v_fmac_f32_e32 v155, v159, v155
	v_div_scale_f32 v159, vcc, v153, v44, v153
	v_mul_f32_e32 v160, v159, v155
	v_fma_f32 v162, -v154, v160, v159
	v_fmac_f32_e32 v160, v162, v155
	v_fma_f32 v154, -v154, v160, v159
	v_div_fmas_f32 v154, v154, v155, v160
	v_div_fixup_f32 v191, v154, v44, v153
	v_add_u32_e32 v154, 0x4800, v69
	v_lshlrev_b32_e32 v44, 16, v152
	v_mul_f32_e32 v152, v7, v156
	v_fmac_f32_e32 v152, v6, v161
	v_fmac_f32_e32 v152, v8, v158
	v_fmac_f32_e32 v152, v9, v44
	v_mul_f32_e32 v153, 0xbfb8aa3b, v152
	v_exp_f32_e32 v153, v153
	s_nop 0
	v_add_f32_e32 v153, 1.0, v153
	v_div_scale_f32 v155, s[10:11], v153, v153, v152
	v_rcp_f32_e32 v157, v155
	s_nop 0
	v_fma_f32 v159, -v155, v157, 1.0
	v_fmac_f32_e32 v157, v159, v157
	v_div_scale_f32 v159, vcc, v152, v153, v152
	v_mul_f32_e32 v160, v159, v157
	v_fma_f32 v161, -v155, v160, v159
	v_fmac_f32_e32 v160, v161, v157
	v_fma_f32 v155, -v155, v160, v159
	v_div_fmas_f32 v155, v155, v157, v160
	v_div_fixup_f32 v192, v155, v153, v152
	v_mul_f32_e32 v152, v7, v158
	v_fmac_f32_e32 v152, v6, v156
	v_fmac_f32_e32 v152, v8, v44
	v_fmac_f32_e32 v152, v9, v59
	v_mul_f32_e32 v153, 0xbfb8aa3b, v152
	v_exp_f32_e32 v153, v153
	s_nop 0
	v_add_f32_e32 v153, 1.0, v153
	v_div_scale_f32 v156, s[10:11], v153, v153, v152
	v_rcp_f32_e32 v157, v156
	s_nop 0
	v_fma_f32 v159, -v156, v157, 1.0
	v_fmac_f32_e32 v157, v159, v157
; __device__ __forceinline__ float bf2f(u16 h) { return __uint_as_float(((unsigned)h) << 16); }
; __device__ __forceinline__ float silu(float y) { return y / (1.f + __expf(-y)); }
; __device__ void ph_dnpre(const P& p, float* lds) {
;     ...
;       for (int arr = 0; arr < 3; ++arr) {
;         const int ch = arr * 512 + h * 64 + lane;
;         const float w0 = p.conv_w[ch], w1 = p.conv_w[1536 + ch], w2 = p.conv_w[3072 + ch], w3 = p.conv_w[4608 + ch];
;         float* dst = arr == 0 ? B0 : (arr == 1 ? B1 : B2);
; #pragma unroll
;         for (int i = 0; i < 16; ++i) {
;           float y = silu(w0 * bf2f(xr[arr][i]) + w1 * bf2f(xr[arr][i + 1]) + w2 * bf2f(xr[arr][i + 2]) + w3 * bf2f(xr[arr][i + 3]));
	v_div_scale_f32 v159, vcc, v152, v153, v152
	v_mul_f32_e32 v160, v159, v157
	v_fma_f32 v161, -v156, v160, v159
	v_fmac_f32_e32 v160, v161, v157
	v_fma_f32 v156, -v156, v160, v159
	v_div_fmas_f32 v156, v156, v157, v160
	v_div_fixup_f32 v193, v156, v153, v152
	v_mul_f32_e32 v152, v7, v44
	v_fmac_f32_e32 v152, v6, v158
	v_fmac_f32_e32 v152, v8, v59
	v_fmac_f32_e32 v152, v9, v151
	v_mul_f32_e32 v153, 0xbfb8aa3b, v152
	v_exp_f32_e32 v153, v153
	s_nop 0
	v_add_f32_e32 v153, 1.0, v153
	v_div_scale_f32 v154, s[10:11], v153, v153, v152
	v_rcp_f32_e32 v155, v154
	s_nop 0
	v_fma_f32 v156, -v154, v155, 1.0
	v_fmac_f32_e32 v155, v156, v155
	v_div_scale_f32 v156, vcc, v152, v153, v152
	v_mul_f32_e32 v157, v156, v155
	v_fma_f32 v158, -v154, v157, v156
	v_fmac_f32_e32 v157, v158, v155
	v_fma_f32 v154, -v154, v157, v156
	v_div_fmas_f32 v154, v154, v155, v157
	v_div_fixup_f32 v194, v154, v153, v152
	v_lshlrev_b32_e32 v155, 16, v39
	v_mul_f32_e32 v39, v7, v59
	s_nop 1
	v_fmac_f32_e32 v39, v6, v44
	v_fmac_f32_e32 v39, v8, v151
	s_nop 0
	v_fmac_f32_e32 v39, v9, v155
	v_mul_f32_e32 v44, 0xbfb8aa3b, v39
	s_nop 0
	v_exp_f32_e32 v44, v44
	s_nop 0
	s_nop 0
	v_add_f32_e32 v44, 1.0, v44
	s_nop 4
	v_div_scale_f32 v152, s[10:11], v44, v44, v39
	v_rcp_f32_e32 v153, v152
	s_nop 0
	v_fma_f32 v156, -v152, v153, 1.0
	v_fmac_f32_e32 v153, v156, v153
	v_div_scale_f32 v156, vcc, v39, v44, v39
	v_mul_f32_e32 v157, v156, v153
	v_fma_f32 v158, -v152, v157, v156
	v_fmac_f32_e32 v157, v158, v153
	v_fma_f32 v152, -v152, v157, v156
	v_div_fmas_f32 v152, v152, v153, v157
	v_div_fixup_f32 v195, v152, v44, v39
	v_lshlrev_b32_e32 v152, 16, v38
	v_mul_f32_e32 v38, v7, v151
	v_fmac_f32_e32 v38, v6, v59
	v_fmac_f32_e32 v38, v8, v155
	v_add_u32_e32 v44, 0x4c00, v69
	s_nop 0
	v_fmac_f32_e32 v38, v9, v152
	s_nop 0
	v_mul_f32_e32 v39, 0xbfb8aa3b, v38
	v_exp_f32_e32 v39, v39
	s_nop 0
	v_add_f32_e32 v39, 1.0, v39
	v_div_scale_f32 v59, s[10:11], v39, v39, v38
	v_rcp_f32_e32 v153, v59
	s_nop 0
	v_fma_f32 v154, -v59, v153, 1.0
	v_fmac_f32_e32 v153, v154, v153
	v_div_scale_f32 v154, vcc, v38, v39, v38
	v_mul_f32_e32 v156, v154, v153
	v_fma_f32 v157, -v59, v156, v154
	v_fmac_f32_e32 v156, v157, v153
	v_fma_f32 v59, -v59, v156, v154
	v_div_fmas_f32 v59, v59, v153, v156
	v_div_fixup_f32 v196, v59, v39, v38
	v_lshlrev_b32_e32 v153, 16, v37
	v_mul_f32_e32 v37, v7, v155
	s_nop 1
	v_fmac_f32_e32 v37, v6, v151
	v_fmac_f32_e32 v37, v8, v152
	s_nop 0
	v_fmac_f32_e32 v37, v9, v153
	s_nop 0
	s_nop 3
	v_mul_f32_e32 v38, 0xbfb8aa3b, v37
	v_exp_f32_e32 v38, v38
	s_nop 0
	v_add_f32_e32 v38, 1.0, v38
	v_div_scale_f32 v39, s[10:11], v38, v38, v37
	v_rcp_f32_e32 v151, v39
	s_nop 0
	v_fma_f32 v154, -v39, v151, 1.0
	v_fmac_f32_e32 v151, v154, v151
	v_div_scale_f32 v154, vcc, v37, v38, v37
	v_mul_f32_e32 v156, v154, v151
	v_fma_f32 v157, -v39, v156, v154
	v_fmac_f32_e32 v156, v157, v151
	v_fma_f32 v39, -v39, v156, v154
	v_div_fmas_f32 v39, v39, v151, v156
	v_div_fixup_f32 v197, v39, v38, v37
	v_lshlrev_b32_e32 v38, 16, v36
	v_mul_f32_e32 v36, v7, v152
	v_fmac_f32_e32 v36, v6, v155
	v_fmac_f32_e32 v36, v8, v153
	v_fmac_f32_e32 v36, v9, v38
	s_nop 0
	v_mul_f32_e32 v37, 0xbfb8aa3b, v36
	v_exp_f32_e32 v37, v37
	s_nop 0
	v_add_f32_e32 v37, 1.0, v37
	v_div_scale_f32 v39, s[10:11], v37, v37, v36
	v_rcp_f32_e32 v44, v39
	s_nop 0
	v_fma_f32 v59, -v39, v44, 1.0
	v_fmac_f32_e32 v44, v59, v44
	v_div_scale_f32 v59, vcc, v36, v37, v36
	v_mul_f32_e32 v151, v59, v44
	v_fma_f32 v154, -v39, v151, v59
	v_fmac_f32_e32 v151, v154, v44
	v_fma_f32 v39, -v39, v151, v59
	v_div_fmas_f32 v39, v39, v44, v151
	v_div_fixup_f32 v198, v39, v37, v36
	v_lshlrev_b32_e32 v44, 16, v35
	v_mul_f32_e32 v35, v7, v153
	s_nop 1
	v_fmac_f32_e32 v35, v6, v152
	v_fmac_f32_e32 v35, v8, v38
	s_nop 0
	v_fmac_f32_e32 v35, v9, v44
	s_nop 0
	s_nop 3
	v_mul_f32_e32 v36, 0xbfb8aa3b, v35
	v_exp_f32_e32 v36, v36
	s_nop 0
	v_add_f32_e32 v36, 1.0, v36
	v_div_scale_f32 v37, s[10:11], v36, v36, v35
	v_rcp_f32_e32 v59, v37
	s_nop 0
	v_fma_f32 v151, -v37, v59, 1.0
	v_fmac_f32_e32 v59, v151, v59
	v_div_scale_f32 v151, vcc, v35, v36, v35
	v_mul_f32_e32 v152, v151, v59
	v_fma_f32 v154, -v37, v152, v151
	v_fmac_f32_e32 v152, v154, v59
	v_fma_f32 v37, -v37, v152, v151
	v_div_fmas_f32 v37, v37, v59, v152
	v_div_fixup_f32 v199, v37, v36, v35
	v_lshlrev_b32_e32 v37, 16, v34
	v_mul_f32_e32 v34, v7, v38
	v_fmac_f32_e32 v34, v6, v153
	v_fmac_f32_e32 v34, v8, v44
	v_add_u32_e32 v36, 0x5000, v69
	s_nop 0
	v_fmac_f32_e32 v34, v9, v37
	s_nop 0
	v_mul_f32_e32 v35, 0xbfb8aa3b, v34
	v_exp_f32_e32 v35, v35
	v_mul_f32_e32 v7, v7, v44
	v_fmac_f32_e32 v7, v6, v38
	v_fmac_f32_e32 v7, v8, v37
	v_add_f32_e32 v35, 1.0, v35
	v_div_scale_f32 v39, s[10:11], v35, v35, v34
	v_rcp_f32_e32 v59, v39
	v_lshlrev_b32_e32 v6, 16, v33
	v_fmac_f32_e32 v7, v9, v6
	v_mul_f32_e32 v6, 0xbfb8aa3b, v7
	v_fma_f32 v151, -v39, v59, 1.0
	v_fmac_f32_e32 v59, v151, v59
	v_div_scale_f32 v151, vcc, v34, v35, v34
	v_mul_f32_e32 v152, v151, v59
	v_fma_f32 v153, -v39, v152, v151
	v_fmac_f32_e32 v152, v153, v59
	v_fma_f32 v39, -v39, v152, v151
	v_div_fmas_f32 v39, v39, v59, v152
	v_div_fixup_f32 v200, v39, v35, v34
	v_exp_f32_e32 v6, v6
	s_nop 0
	s_nop 1
	v_add_f32_e32 v6, 1.0, v6
	s_nop 0
	s_nop 3
	v_div_scale_f32 v8, s[10:11], v6, v6, v7
	s_nop 3
	v_rcp_f32_e32 v9, v8
	s_nop 1
	v_fma_f32 v33, -v8, v9, 1.0
	v_fmac_f32_e32 v9, v33, v9
	v_div_scale_f32 v33, vcc, v7, v6, v7
	s_nop 1
	v_mul_f32_e32 v35, v33, v9
	v_fma_f32 v37, -v8, v35, v33
	v_fmac_f32_e32 v35, v37, v9
	v_fma_f32 v8, -v8, v35, v33
	v_div_fmas_f32 v8, v8, v9, v35
	v_div_fixup_f32 v201, v8, v6, v7
	v_mul_f32_e32 v202, v186, v186
	v_mul_f32_e32 v203, v187, v187
; __device__ __forceinline__ float bf2f(u16 h) { return __uint_as_float(((unsigned)h) << 16); }
; __device__ __forceinline__ float silu(float y) { return y / (1.f + __expf(-y)); }
; __device__ void ph_dnpre(const P& p, float* lds) {
;     ...
;           float y = silu(w0 * bf2f(xr[arr][i]) + w1 * bf2f(xr[arr][i + 1]) + w2 * bf2f(xr[arr][i + 2]) + w3 * bf2f(xr[arr][i + 3]));
;           if (arr < 2) {
;             float ss = wave_sum(y * y);
;             y *= rsqrtf(ss + EPS) * (arr == 0 ? 0.125f : 1.f);
;           }
;           dst[(w * 16 + i) * LS + lane] = y;
;         }
	v_mul_f32_e32 v204, v188, v188
	v_mul_f32_e32 v205, v189, v189
	v_mul_f32_e32 v206, v190, v190
	v_mul_f32_e32 v207, v191, v191
	v_mul_f32_e32 v208, v192, v192
	v_mul_f32_e32 v209, v193, v193
	v_mul_f32_e32 v210, v194, v194
	v_mul_f32_e32 v211, v195, v195
	v_mul_f32_e32 v212, v196, v196
	v_mul_f32_e32 v213, v197, v197
	v_mul_f32_e32 v214, v198, v198
	v_mul_f32_e32 v215, v199, v199
	v_mul_f32_e32 v216, v200, v200
	v_mul_f32_e32 v217, v201, v201
	v_permlane32_swap_b32 v202, v210
	v_permlane32_swap_b32 v203, v211
	v_permlane32_swap_b32 v204, v212
	v_permlane32_swap_b32 v205, v213
	v_permlane32_swap_b32 v206, v214
	v_permlane32_swap_b32 v207, v215
	v_permlane32_swap_b32 v208, v216
	v_permlane32_swap_b32 v209, v217
	v_add_f32_e32 v202, v202, v210
	v_add_f32_e32 v203, v203, v211
	v_add_f32_e32 v204, v204, v212
	v_add_f32_e32 v205, v205, v213
	v_add_f32_e32 v206, v206, v214
	v_add_f32_e32 v207, v207, v215
	v_add_f32_e32 v208, v208, v216
	v_add_f32_e32 v209, v209, v217
	v_permlane16_swap_b32 v202, v206
	v_permlane16_swap_b32 v203, v207
	v_permlane16_swap_b32 v204, v208
	v_permlane16_swap_b32 v205, v209
	s_mov_b32 s44, 0xff00ff00
	s_mov_b32 s45, 0xff00ff00
	v_add_f32_e32 v202, v202, v206
	v_add_f32_e32 v203, v203, v207
	v_add_f32_e32 v204, v204, v208
	v_add_f32_e32 v205, v205, v209
	v_add_u32_e32 v214, 0x400, v226
	v_add_u32_e32 v215, 0x800, v226
	v_cndmask_b32_e64 v210, v204, v202, s[44:45]
	v_cndmask_b32_e64 v211, v202, v204, s[44:45]
	v_cndmask_b32_e64 v212, v205, v203, s[44:45]
	v_cndmask_b32_e64 v213, v203, v205, s[44:45]
	v_add_u32_e32 v216, 0xc00, v226
	s_nop 0
	v_add_f32_dpp v202, v210, v211 row_ror:8 row_mask:0xf bank_mask:0xf
	v_add_f32_dpp v203, v212, v213 row_ror:8 row_mask:0xf bank_mask:0xf
	s_nop 0
	v_add_f32_dpp v202, v202, v202 quad_perm:[1,0,3,2] row_mask:0xf bank_mask:0xf
	v_add_f32_dpp v203, v203, v203 quad_perm:[1,0,3,2] row_mask:0xf bank_mask:0xf
	s_nop 0
	v_add_f32_dpp v202, v202, v202 quad_perm:[2,3,0,1] row_mask:0xf bank_mask:0xf
	v_add_f32_dpp v203, v203, v203 quad_perm:[2,3,0,1] row_mask:0xf bank_mask:0xf
	s_nop 0
	v_add_f32_dpp v202, v202, v202 row_half_mirror row_mask:0xf bank_mask:0xf
	v_add_f32_dpp v203, v203, v203 row_half_mirror row_mask:0xf bank_mask:0xf
	v_add_f32_e32 v202, 0x358637bd, v202
	v_add_f32_e32 v203, 0x358637bd, v203
	v_rsq_f32_e32 v202, v202
	v_rsq_f32_e32 v203, v203
	s_nop 0
	v_readlane_b32 s44, v202, 0
	v_readlane_b32 s45, v203, 0
	v_readlane_b32 s10, v202, 8
	v_readlane_b32 s11, v203, 8
	v_mul_f32_e32 v186, s44, v186
	v_mul_f32_e32 v187, s45, v187
	v_mul_f32_e32 v188, s10, v188
	v_mul_f32_e32 v189, s11, v189
	ds_write2_b32 v226, v186, v187 offset1:68
	ds_write2_b32 v226, v188, v189 offset0:136 offset1:204
	v_readlane_b32 s44, v202, 16
	v_readlane_b32 s45, v203, 16
	v_readlane_b32 s10, v202, 24
	v_readlane_b32 s11, v203, 24
	v_mul_f32_e32 v190, s44, v190
	v_mul_f32_e32 v191, s45, v191
	v_mul_f32_e32 v192, s10, v192
	v_mul_f32_e32 v193, s11, v193
	ds_write2_b32 v214, v190, v191 offset0:16 offset1:84
	ds_write2_b32 v214, v192, v193 offset0:152 offset1:220
	v_readlane_b32 s44, v202, 32
	v_readlane_b32 s45, v203, 32
	v_readlane_b32 s10, v202, 40
	v_readlane_b32 s11, v203, 40
	v_mul_f32_e32 v194, s44, v194
	v_mul_f32_e32 v195, s45, v195
	v_mul_f32_e32 v196, s10, v196
	v_mul_f32_e32 v197, s11, v197
	ds_write2_b32 v215, v194, v195 offset0:32 offset1:100
	ds_write2_b32 v215, v196, v197 offset0:168 offset1:236
	v_readlane_b32 s44, v202, 48
	v_readlane_b32 s45, v203, 48
	v_readlane_b32 s10, v202, 56
	v_readlane_b32 s11, v203, 56
	v_mul_f32_e32 v198, s44, v198
	v_mul_f32_e32 v199, s45, v199
	v_mul_f32_e32 v200, s10, v200
	v_mul_f32_e32 v201, s11, v201
	ds_write2_b32 v216, v198, v199 offset0:48 offset1:116
	ds_write2_b32 v216, v200, v201 offset0:184 offset1:252
	global_load_dword v0, v[0:1], off
	s_nop 0
	global_load_dword v6, v[10:11], off offset:2048
	global_load_dword v1, v[2:3], off
	s_nop 0
	global_load_dword v2, v[4:5], off offset:2048
	v_lshlrev_b32_e32 v7, 16, v29
	v_lshlrev_b32_e32 v5, 16, v25
	v_lshlrev_b32_e32 v3, 16, v31
	v_lshlrev_b32_e32 v4, 16, v32
	s_waitcnt vmcnt(2)
	v_mul_f32_e32 v8, v6, v7
	v_fmac_f32_e32 v8, v0, v5
	s_waitcnt vmcnt(1)
	v_fmac_f32_e32 v8, v1, v3
	s_waitcnt vmcnt(0)
	v_fmac_f32_e32 v8, v2, v4
	v_mul_f32_e32 v5, 0xbfb8aa3b, v8
	v_exp_f32_e32 v5, v5
	s_nop 0
	v_add_f32_e32 v5, 1.0, v5
	v_div_scale_f32 v9, s[10:11], v5, v5, v8
	v_rcp_f32_e32 v10, v9
	s_nop 0
	v_fma_f32 v11, -v9, v10, 1.0
	v_fmac_f32_e32 v10, v11, v10
	v_div_scale_f32 v11, vcc, v8, v5, v8
	v_mul_f32_e32 v25, v11, v10
	v_fma_f32 v29, -v9, v25, v11
	v_fmac_f32_e32 v25, v29, v10
	v_fma_f32 v9, -v9, v25, v11
	v_div_fmas_f32 v9, v9, v10, v25
	v_div_fixup_f32 v5, v9, v5, v8
	v_mul_f32_e32 v9, v6, v3
	v_fmac_f32_e32 v9, v0, v7
	v_lshlrev_b32_e32 v8, 16, v30
	v_fmac_f32_e32 v9, v1, v4
	v_fmac_f32_e32 v9, v2, v8
	v_mul_f32_e32 v7, 0xbfb8aa3b, v9
	v_exp_f32_e32 v7, v7
	s_nop 0
	v_add_f32_e32 v7, 1.0, v7
	v_div_scale_f32 v10, s[10:11], v7, v7, v9
	v_rcp_f32_e32 v11, v10
	s_nop 0
	v_fma_f32 v25, -v10, v11, 1.0
	v_fmac_f32_e32 v11, v25, v11
	v_div_scale_f32 v25, vcc, v9, v7, v9
	v_mul_f32_e32 v29, v25, v11
	v_fma_f32 v30, -v10, v29, v25
	v_fmac_f32_e32 v29, v30, v11
	v_fma_f32 v10, -v10, v29, v25
	v_div_fmas_f32 v10, v10, v11, v29
	v_div_fixup_f32 v7, v10, v7, v9
	v_add_u32_e32 v9, 0x8800, v69
	ds_write2_b32 v9, v5, v7 offset1:68
	v_mul_f32_e32 v7, v6, v4
	v_fmac_f32_e32 v7, v0, v3
	v_lshlrev_b32_e32 v5, 16, v28
	v_fmac_f32_e32 v7, v1, v8
	v_fmac_f32_e32 v7, v2, v5
	v_mul_f32_e32 v3, 0xbfb8aa3b, v7
	v_exp_f32_e32 v3, v3
	s_nop 0
	v_add_f32_e32 v3, 1.0, v3
	v_div_scale_f32 v10, s[10:11], v3, v3, v7
	v_rcp_f32_e32 v11, v10
; __device__ __forceinline__ float bf2f(u16 h) { return __uint_as_float(((unsigned)h) << 16); }
; __device__ __forceinline__ float silu(float y) { return y / (1.f + __expf(-y)); }
; __device__ void ph_dnpre(const P& p, float* lds) {
;     ...
; #pragma unroll
;         for (int i = 0; i < 16; ++i) {
;           float y = silu(w0 * bf2f(xr[arr][i]) + w1 * bf2f(xr[arr][i + 1]) + w2 * bf2f(xr[arr][i + 2]) + w3 * bf2f(xr[arr][i + 3]));
;           if (arr < 2) {
;             float ss = wave_sum(y * y);
;             y *= rsqrtf(ss + EPS) * (arr == 0 ? 0.125f : 1.f);
;           }
;           dst[(w * 16 + i) * LS + lane] = y;
	s_nop 0
	v_fma_f32 v25, -v10, v11, 1.0
	v_fmac_f32_e32 v11, v25, v11
	v_div_scale_f32 v25, vcc, v7, v3, v7
	v_mul_f32_e32 v28, v25, v11
	v_fma_f32 v29, -v10, v28, v25
	v_fmac_f32_e32 v28, v29, v11
	v_fma_f32 v10, -v10, v28, v25
	v_div_fmas_f32 v10, v10, v11, v28
	v_div_fixup_f32 v3, v10, v3, v7
	v_mul_f32_e32 v10, v6, v8
	v_fmac_f32_e32 v10, v0, v4
	v_lshlrev_b32_e32 v7, 16, v27
	v_fmac_f32_e32 v10, v1, v5
	v_fmac_f32_e32 v10, v2, v7
	v_mul_f32_e32 v4, 0xbfb8aa3b, v10
	v_exp_f32_e32 v4, v4
	s_nop 0
	v_add_f32_e32 v4, 1.0, v4
	v_div_scale_f32 v11, s[10:11], v4, v4, v10
	v_rcp_f32_e32 v25, v11
	s_nop 0
	v_fma_f32 v27, -v11, v25, 1.0
	v_fmac_f32_e32 v25, v27, v25
	v_div_scale_f32 v27, vcc, v10, v4, v10
	v_mul_f32_e32 v28, v27, v25
	v_fma_f32 v29, -v11, v28, v27
	v_fmac_f32_e32 v28, v29, v25
	v_fma_f32 v11, -v11, v28, v27
	v_div_fmas_f32 v11, v11, v25, v28
	v_div_fixup_f32 v4, v11, v4, v10
	ds_write2_b32 v9, v3, v4 offset0:136 offset1:204
	v_mul_f32_e32 v4, v6, v5
	v_fmac_f32_e32 v4, v0, v8
	v_lshlrev_b32_e32 v3, 16, v26
	v_fmac_f32_e32 v4, v1, v7
	v_fmac_f32_e32 v4, v2, v3
	v_mul_f32_e32 v8, 0xbfb8aa3b, v4
	v_exp_f32_e32 v8, v8
	s_nop 0
	v_add_f32_e32 v8, 1.0, v8
	v_div_scale_f32 v9, s[10:11], v8, v8, v4
	v_rcp_f32_e32 v10, v9
	s_nop 0
	v_fma_f32 v11, -v9, v10, 1.0
	v_fmac_f32_e32 v10, v11, v10
	v_div_scale_f32 v11, vcc, v4, v8, v4
	v_mul_f32_e32 v25, v11, v10
	v_fma_f32 v26, -v9, v25, v11
	v_fmac_f32_e32 v25, v26, v10
	v_fma_f32 v9, -v9, v25, v11
	v_div_fmas_f32 v9, v9, v10, v25
	v_div_fixup_f32 v4, v9, v8, v4
	v_mul_f32_e32 v9, v6, v7
	v_fmac_f32_e32 v9, v0, v5
	v_lshlrev_b32_e32 v8, 16, v24
	v_fmac_f32_e32 v9, v1, v3
	v_fmac_f32_e32 v9, v2, v8
	v_mul_f32_e32 v5, 0xbfb8aa3b, v9
	v_exp_f32_e32 v5, v5
	s_nop 0
	v_add_f32_e32 v5, 1.0, v5
	v_div_scale_f32 v10, s[10:11], v5, v5, v9
	v_rcp_f32_e32 v11, v10
	s_nop 0
	v_fma_f32 v24, -v10, v11, 1.0
	v_fmac_f32_e32 v11, v24, v11
	v_div_scale_f32 v24, vcc, v9, v5, v9
	v_mul_f32_e32 v25, v24, v11
	v_fma_f32 v26, -v10, v25, v24
	v_fmac_f32_e32 v25, v26, v11
	v_fma_f32 v10, -v10, v25, v24
	v_div_fmas_f32 v10, v10, v11, v25
	v_div_fixup_f32 v5, v10, v5, v9
	v_add_u32_e32 v9, 0x8c00, v69
	ds_write2_b32 v9, v4, v5 offset0:16 offset1:84
	v_mul_f32_e32 v5, v6, v3
	v_fmac_f32_e32 v5, v0, v7
	v_lshlrev_b32_e32 v4, 16, v23
	v_fmac_f32_e32 v5, v1, v8
	v_fmac_f32_e32 v5, v2, v4
	v_mul_f32_e32 v7, 0xbfb8aa3b, v5
	v_exp_f32_e32 v7, v7
	s_nop 0
	v_add_f32_e32 v7, 1.0, v7
	v_div_scale_f32 v10, s[10:11], v7, v7, v5
	v_rcp_f32_e32 v11, v10
	s_nop 0
	v_fma_f32 v23, -v10, v11, 1.0
	v_fmac_f32_e32 v11, v23, v11
	v_div_scale_f32 v23, vcc, v5, v7, v5
	v_mul_f32_e32 v24, v23, v11
	v_fma_f32 v25, -v10, v24, v23
	v_fmac_f32_e32 v24, v25, v11
	v_fma_f32 v10, -v10, v24, v23
	v_div_fmas_f32 v10, v10, v11, v24
	v_div_fixup_f32 v5, v10, v7, v5
	v_mul_f32_e32 v10, v6, v8
	v_fmac_f32_e32 v10, v0, v3
	v_lshlrev_b32_e32 v7, 16, v22
	v_fmac_f32_e32 v10, v1, v4
	v_fmac_f32_e32 v10, v2, v7
	v_mul_f32_e32 v3, 0xbfb8aa3b, v10
	v_exp_f32_e32 v3, v3
	s_nop 0
	v_add_f32_e32 v3, 1.0, v3
	v_div_scale_f32 v11, s[10:11], v3, v3, v10
	v_rcp_f32_e32 v22, v11
	s_nop 0
	v_fma_f32 v23, -v11, v22, 1.0
	v_fmac_f32_e32 v22, v23, v22
	v_div_scale_f32 v23, vcc, v10, v3, v10
	v_mul_f32_e32 v24, v23, v22
	v_fma_f32 v25, -v11, v24, v23
	v_fmac_f32_e32 v24, v25, v22
	v_fma_f32 v11, -v11, v24, v23
	v_div_fmas_f32 v11, v11, v22, v24
	v_div_fixup_f32 v3, v11, v3, v10
	ds_write2_b32 v9, v5, v3 offset0:152 offset1:220
	v_mul_f32_e32 v5, v6, v4
	v_fmac_f32_e32 v5, v0, v8
	v_lshlrev_b32_e32 v3, 16, v21
	v_fmac_f32_e32 v5, v1, v7
	v_fmac_f32_e32 v5, v2, v3
	v_mul_f32_e32 v8, 0xbfb8aa3b, v5
	v_exp_f32_e32 v8, v8
	s_nop 0
	v_add_f32_e32 v8, 1.0, v8
	v_div_scale_f32 v9, s[10:11], v8, v8, v5
	v_rcp_f32_e32 v10, v9
	s_nop 0
	v_fma_f32 v11, -v9, v10, 1.0
	v_fmac_f32_e32 v10, v11, v10
	v_div_scale_f32 v11, vcc, v5, v8, v5
	v_mul_f32_e32 v21, v11, v10
	v_fma_f32 v22, -v9, v21, v11
	v_fmac_f32_e32 v21, v22, v10
	v_fma_f32 v9, -v9, v21, v11
	v_div_fmas_f32 v9, v9, v10, v21
	v_div_fixup_f32 v5, v9, v8, v5
	v_mul_f32_e32 v9, v6, v7
	v_fmac_f32_e32 v9, v0, v4
	v_lshlrev_b32_e32 v8, 16, v20
	v_fmac_f32_e32 v9, v1, v3
	v_fmac_f32_e32 v9, v2, v8
	v_mul_f32_e32 v4, 0xbfb8aa3b, v9
	v_exp_f32_e32 v4, v4
	s_nop 0
	v_add_f32_e32 v4, 1.0, v4
	v_div_scale_f32 v10, s[10:11], v4, v4, v9
	v_rcp_f32_e32 v11, v10
	s_nop 0
	v_fma_f32 v20, -v10, v11, 1.0
	v_fmac_f32_e32 v11, v20, v11
	v_div_scale_f32 v20, vcc, v9, v4, v9
	v_mul_f32_e32 v21, v20, v11
	v_fma_f32 v22, -v10, v21, v20
	v_fmac_f32_e32 v21, v22, v11
	v_fma_f32 v10, -v10, v21, v20
	v_div_fmas_f32 v10, v10, v11, v21
	v_div_fixup_f32 v4, v10, v4, v9
	v_add_u32_e32 v9, 0x9000, v69
	ds_write2_b32 v9, v5, v4 offset0:32 offset1:100
	v_mul_f32_e32 v5, v6, v3
	v_fmac_f32_e32 v5, v0, v7
	v_lshlrev_b32_e32 v4, 16, v19
	v_fmac_f32_e32 v5, v1, v8
	v_fmac_f32_e32 v5, v2, v4
	v_mul_f32_e32 v7, 0xbfb8aa3b, v5
	v_exp_f32_e32 v7, v7
	s_nop 0
	v_add_f32_e32 v7, 1.0, v7
	v_div_scale_f32 v10, s[10:11], v7, v7, v5
	v_rcp_f32_e32 v11, v10
	s_nop 0
	v_fma_f32 v19, -v10, v11, 1.0
	v_fmac_f32_e32 v11, v19, v11
	v_div_scale_f32 v19, vcc, v5, v7, v5
	v_mul_f32_e32 v20, v19, v11
	v_fma_f32 v21, -v10, v20, v19
	v_fmac_f32_e32 v20, v21, v11
	v_fma_f32 v10, -v10, v20, v19
	v_div_fmas_f32 v10, v10, v11, v20
	v_div_fixup_f32 v5, v10, v7, v5
	v_mul_f32_e32 v10, v6, v8
	v_fmac_f32_e32 v10, v0, v3
	v_lshlrev_b32_e32 v7, 16, v18
	v_fmac_f32_e32 v10, v1, v4
	v_fmac_f32_e32 v10, v2, v7
	v_mul_f32_e32 v3, 0xbfb8aa3b, v10
	v_exp_f32_e32 v3, v3
	s_nop 0
	v_add_f32_e32 v3, 1.0, v3
	v_div_scale_f32 v11, s[10:11], v3, v3, v10
	v_rcp_f32_e32 v18, v11
	s_nop 0
	v_fma_f32 v19, -v11, v18, 1.0
; __device__ __forceinline__ float bf2f(u16 h) { return __uint_as_float(((unsigned)h) << 16); }
; __device__ __forceinline__ float silu(float y) { return y / (1.f + __expf(-y)); }
; __device__ __forceinline__ float softplusf(float x) { return x > 20.f ? x : log1pf(__expf(x)); }
; __device__ void ph_dnpre(const P& p, float* lds) {
;     ...
; #pragma unroll
;         for (int i = 0; i < 16; ++i) {
;           float y = silu(w0 * bf2f(xr[arr][i]) + w1 * bf2f(xr[arr][i + 1]) + w2 * bf2f(xr[arr][i + 2]) + w3 * bf2f(xr[arr][i + 3]));
;           if (arr < 2) {
;             float ss = wave_sum(y * y);
;             y *= rsqrtf(ss + EPS) * (arr == 0 ? 0.125f : 1.f);
;           }
;           dst[(w * 16 + i) * LS + lane] = y;
;         }
;       }
;       if (w == 0) {
;         float g = -__expf(p.a_log[h]) * softplusf(ar_raw + p.dt_bias[h]);
	v_fmac_f32_e32 v18, v19, v18
	v_div_scale_f32 v19, vcc, v10, v3, v10
	v_mul_f32_e32 v20, v19, v18
	v_fma_f32 v21, -v11, v20, v19
	v_fmac_f32_e32 v20, v21, v18
	v_fma_f32 v11, -v11, v20, v19
	v_div_fmas_f32 v11, v11, v18, v20
	v_div_fixup_f32 v3, v11, v3, v10
	ds_write2_b32 v9, v5, v3 offset0:168 offset1:236
	v_mul_f32_e32 v5, v6, v4
	v_fmac_f32_e32 v5, v0, v8
	v_lshlrev_b32_e32 v3, 16, v17
	v_fmac_f32_e32 v5, v1, v7
	v_fmac_f32_e32 v5, v2, v3
	v_mul_f32_e32 v8, 0xbfb8aa3b, v5
	v_exp_f32_e32 v8, v8
	s_nop 0
	v_add_f32_e32 v8, 1.0, v8
	v_div_scale_f32 v9, s[10:11], v8, v8, v5
	v_rcp_f32_e32 v10, v9
	s_nop 0
	v_fma_f32 v11, -v9, v10, 1.0
	v_fmac_f32_e32 v10, v11, v10
	v_div_scale_f32 v11, vcc, v5, v8, v5
	v_mul_f32_e32 v17, v11, v10
	v_fma_f32 v18, -v9, v17, v11
	v_fmac_f32_e32 v17, v18, v10
	v_fma_f32 v9, -v9, v17, v11
	v_div_fmas_f32 v9, v9, v10, v17
	v_div_fixup_f32 v5, v9, v8, v5
	v_mul_f32_e32 v9, v6, v7
	v_fmac_f32_e32 v9, v0, v4
	v_lshlrev_b32_e32 v8, 16, v16
	v_fmac_f32_e32 v9, v1, v3
	v_fmac_f32_e32 v9, v2, v8
	v_mul_f32_e32 v4, 0xbfb8aa3b, v9
	v_exp_f32_e32 v4, v4
	s_nop 0
	v_add_f32_e32 v4, 1.0, v4
	v_div_scale_f32 v10, s[10:11], v4, v4, v9
	v_rcp_f32_e32 v11, v10
	s_nop 0
	v_fma_f32 v16, -v10, v11, 1.0
	v_fmac_f32_e32 v11, v16, v11
	v_div_scale_f32 v16, vcc, v9, v4, v9
	v_mul_f32_e32 v17, v16, v11
	v_fma_f32 v18, -v10, v17, v16
	v_fmac_f32_e32 v17, v18, v11
	v_fma_f32 v10, -v10, v17, v16
	v_div_fmas_f32 v10, v10, v11, v17
	v_div_fixup_f32 v4, v10, v4, v9
	v_add_u32_e32 v9, 0x9400, v69
	ds_write2_b32 v9, v5, v4 offset0:48 offset1:116
	v_mul_f32_e32 v4, v6, v3
	v_fmac_f32_e32 v4, v0, v7
	v_fmac_f32_e32 v4, v1, v8
	v_lshlrev_b32_e32 v5, 16, v15
	v_fmac_f32_e32 v4, v2, v5
	v_mul_f32_e32 v7, 0xbfb8aa3b, v4
	v_exp_f32_e32 v7, v7
	v_mul_f32_e32 v6, v6, v8
	v_fmac_f32_e32 v6, v0, v3
	v_fmac_f32_e32 v6, v1, v5
	v_lshlrev_b32_e32 v0, 16, v14
	v_fmac_f32_e32 v6, v2, v0
	v_add_f32_e32 v7, 1.0, v7
	v_mul_f32_e32 v0, 0xbfb8aa3b, v6
	v_div_scale_f32 v10, s[10:11], v7, v7, v4
	v_exp_f32_e32 v0, v0
	v_rcp_f32_e32 v11, v10
	v_add_f32_e32 v0, 1.0, v0
	v_fma_f32 v15, -v10, v11, 1.0
	v_div_scale_f32 v1, s[10:11], v0, v0, v6
	v_fmac_f32_e32 v11, v15, v11
	v_div_scale_f32 v15, vcc, v4, v7, v4
	v_rcp_f32_e32 v2, v1
	v_mul_f32_e32 v16, v15, v11
	v_fma_f32 v17, -v10, v16, v15
	v_fmac_f32_e32 v16, v17, v11
	v_fma_f32 v10, -v10, v16, v15
	v_fma_f32 v3, -v1, v2, 1.0
	v_div_fmas_f32 v10, v10, v11, v16
	v_fmac_f32_e32 v2, v3, v2
	v_div_scale_f32 v3, vcc, v6, v0, v6
	v_mul_f32_e32 v5, v3, v2
	v_div_fixup_f32 v4, v10, v7, v4
	v_fma_f32 v7, -v1, v5, v3
	v_fmac_f32_e32 v5, v7, v2
	v_fma_f32 v1, -v1, v5, v3
	v_div_fmas_f32 v1, v1, v2, v5
	v_div_fixup_f32 v0, v1, v0, v6
	ds_write2_b32 v9, v4, v0 offset0:184 offset1:252
	s_and_saveexec_b64 s[56:57], s[0:1]
	s_cbranch_execz .LBB0_180
	v_readlane_b32 s76, v228, 33
	v_readlane_b32 s80, v228, 37
	v_readlane_b32 s81, v228, 38
	s_lshl_b32 s3, s3, 2
	v_readlane_b32 s82, v228, 39
	v_readlane_b32 s83, v228, 40
	v_readlane_b32 s84, v228, 41
	v_readlane_b32 s85, v228, 42
	v_readlane_b32 s86, v228, 43
	v_readlane_b32 s87, v228, 44
	v_readlane_b32 s88, v228, 45
	v_readlane_b32 s89, v228, 46
	s_mov_b64 s[44:45], s[80:81]
	v_mov_b32_e32 v0, s3
	s_mov_b64 s[50:51], s[86:87]
	s_mov_b64 s[48:49], s[84:85]
	global_load_dword v1, v0, s[50:51]
	s_nop 0
	global_load_dword v0, v0, s[48:49]
	v_lshlrev_b32_e32 v2, 16, v13
	s_mov_b32 s3, 0x41a00000
	v_readlane_b32 s77, v228, 34
	v_readlane_b32 s78, v228, 35
	v_readlane_b32 s79, v228, 36
	v_readlane_b32 s90, v228, 47
	v_readlane_b32 s91, v228, 48
	s_mov_b64 s[46:47], s[82:83]
	s_mov_b64 s[52:53], s[88:89]
	s_waitcnt vmcnt(1)
	v_add_f32_e32 v1, v1, v2
	v_cmp_nlt_f32_e32 vcc, s3, v1
	s_and_saveexec_b64 s[96:97], vcc
	s_cbranch_execz .LBB0_179
; __device__ __forceinline__ float softplusf(float x) { return x > 20.f ? x : log1pf(__expf(x)); }
; __device__ void ph_dnpre(const P& p, float* lds) {
;     ...
;         float g = -__expf(p.a_log[h]) * softplusf(ar_raw + p.dt_bias[h]);
	v_mul_f32_e32 v1, 0x3fb8aa3b, v1
	v_exp_f32_e32 v1, v1
	s_mov_b32 s3, 0x3f2aaaab
	v_add_f32_e32 v4, 1.0, v1
	v_frexp_mant_f32_e32 v6, v4
	v_cvt_f64_f32_e32 v[2:3], v4
	v_frexp_exp_i32_f64_e32 v2, v[2:3]
	v_cmp_gt_f32_e32 vcc, s3, v6
	v_add_f32_e32 v5, -1.0, v4
	v_sub_f32_e32 v7, v5, v4
	v_subbrev_co_u32_e32 v10, vcc, 0, v2, vcc
	v_sub_u32_e32 v2, 0, v10
	v_sub_f32_e32 v5, v1, v5
	v_add_f32_e32 v7, 1.0, v7
	v_ldexp_f32 v3, v4, v2
	v_add_f32_e32 v5, v5, v7
	v_add_f32_e32 v4, -1.0, v3
	v_add_f32_e32 v6, 1.0, v3
	v_ldexp_f32 v2, v5, v2
	v_add_f32_e32 v5, 1.0, v4
	v_add_f32_e32 v7, -1.0, v6
	v_sub_f32_e32 v5, v3, v5
	v_sub_f32_e32 v3, v3, v7
	v_add_f32_e32 v5, v2, v5
	v_add_f32_e32 v2, v2, v3
	v_add_f32_e32 v11, v6, v2
	v_rcp_f32_e32 v14, v11
	v_sub_f32_e32 v3, v11, v6
	v_sub_f32_e32 v13, v2, v3
	v_add_f32_e32 v3, v4, v5
	v_mul_f32_e32 v16, v3, v14
	v_sub_f32_e32 v2, v3, v4
	v_mul_f32_e32 v4, v11, v16
	v_fma_f32 v6, v16, v11, -v4
	v_fmac_f32_e32 v6, v16, v13
	v_sub_f32_e32 v15, v5, v2
	v_add_f32_e32 v2, v4, v6
	v_sub_f32_e32 v5, v3, v2
	v_pk_add_f32 v[8:9], v[2:3], v[4:5] neg_lo:[0,1] neg_hi:[0,1]
	v_mov_b32_e32 v7, v2
	v_pk_add_f32 v[2:3], v[8:9], v[6:7] neg_lo:[0,1] neg_hi:[0,1]
	s_mov_b32 s3, 0x3f317218
	v_add_f32_e32 v3, v15, v3
	v_add_f32_e32 v2, v2, v3
	v_add_f32_e32 v3, v5, v2
	v_mul_f32_e32 v15, v14, v3
	v_mul_f32_e32 v4, v11, v15
	v_fma_f32 v6, v15, v11, -v4
	v_fmac_f32_e32 v6, v15, v13
	v_sub_f32_e32 v5, v5, v3
	v_add_f32_e32 v11, v2, v5
	v_add_f32_e32 v2, v4, v6
	v_sub_f32_e32 v5, v3, v2
	v_pk_add_f32 v[8:9], v[2:3], v[4:5] neg_lo:[0,1] neg_hi:[0,1]
	v_mov_b32_e32 v7, v2
	v_pk_add_f32 v[2:3], v[8:9], v[6:7] neg_lo:[0,1] neg_hi:[0,1]
	s_nop 0
	v_add_f32_e32 v3, v11, v3
	v_add_f32_e32 v2, v2, v3
	v_add_f32_e32 v3, v16, v15
	v_add_f32_e32 v2, v5, v2
	v_sub_f32_e32 v4, v3, v16
	v_mul_f32_e32 v2, v14, v2
	v_sub_f32_e32 v4, v15, v4
	v_add_f32_e32 v4, v4, v2
	v_add_f32_e32 v6, v3, v4
	v_mul_f32_e32 v7, v6, v6
	v_fmamk_f32 v2, v7, 0x3e9b6dac, v70
	v_fmaak_f32 v59, v7, v2, 0x3f2aaada
	v_cvt_f32_i32_e32 v2, v10
	v_sub_f32_e32 v3, v6, v3
	v_sub_f32_e32 v3, v4, v3
	v_ldexp_f32 v8, v3, 1
	v_mul_f32_e32 v3, v6, v7
	v_ldexp_f32 v5, v6, 1
	v_pk_mul_f32 v[6:7], v[2:3], v[58:59]
	s_nop 0
	v_fma_f32 v4, v2, s3, -v6
	v_fmac_f32_e32 v4, 0xb102e308, v2
	v_pk_add_f32 v[2:3], v[6:7], v[4:5]
	s_mov_b32 s3, 0x7f800000
	v_sub_f32_e32 v5, v3, v5
	v_sub_f32_e32 v5, v7, v5
	v_add_f32_e32 v9, v8, v5
	v_mov_b32_e32 v8, v6
	v_pk_add_f32 v[6:7], v[2:3], v[6:7] neg_lo:[0,1] neg_hi:[0,1]
	v_pk_add_f32 v[10:11], v[2:3], v[8:9]
	v_mov_b32_e32 v5, v2
	v_mov_b32_e32 v7, v11
	v_pk_add_f32 v[14:15], v[4:5], v[6:7] neg_lo:[0,1] neg_hi:[0,1]
	v_pk_add_f32 v[4:5], v[4:5], v[6:7]
	v_mov_b32_e32 v8, v9
	v_pk_add_f32 v[6:7], v[4:5], v[2:3] op_sel:[1,0] op_sel_hi:[0,1] neg_lo:[0,1] neg_hi:[0,1]
	v_pk_add_f32 v[16:17], v[10:11], v[6:7] op_sel_hi:[1,0] neg_lo:[0,1] neg_hi:[0,1]
	v_mov_b32_e32 v10, v11
	v_mov_b32_e32 v11, v5
	v_pk_mov_b32 v[6:7], v[2:3], v[6:7] op_sel:[1,0]
	v_mov_b32_e32 v9, v2
	v_pk_add_f32 v[6:7], v[10:11], v[6:7] neg_lo:[0,1] neg_hi:[0,1]
	v_mov_b32_e32 v16, v14
	v_pk_add_f32 v[2:3], v[8:9], v[6:7] neg_lo:[0,1] neg_hi:[0,1]
	v_mov_b32_e32 v15, v5
	v_pk_add_f32 v[6:7], v[16:17], v[2:3]
	v_cmp_neq_f32_e32 vcc, s3, v1
	v_pk_add_f32 v[8:9], v[6:7], v[6:7] op_sel:[0,1] op_sel_hi:[1,0]
	s_mov_b32 s3, 0x33800000
	v_pk_add_f32 v[4:5], v[4:5], v[8:9] op_sel:[1,0] op_sel_hi:[0,1]
	v_mov_b32_e32 v7, v4
	v_pk_add_f32 v[10:11], v[6:7], v[14:15] neg_lo:[0,1] neg_hi:[0,1]
	v_mov_b32_e32 v3, v8
	v_sub_f32_e32 v5, v6, v10
	v_pk_add_f32 v[2:3], v[2:3], v[10:11] neg_lo:[0,1] neg_hi:[0,1]
	v_sub_f32_e32 v5, v14, v5
	v_add_f32_e32 v2, v2, v5
	v_add_f32_e32 v2, v2, v3
	v_add_f32_e32 v2, v4, v2
	v_cndmask_b32_e32 v2, v92, v2, vcc
	v_cmp_ngt_f32_e32 vcc, -1.0, v1
	s_nop 1
	v_cndmask_b32_e32 v2, v93, v2, vcc
	v_cmp_neq_f32_e32 vcc, -1.0, v1
	s_nop 1
	v_cndmask_b32_e32 v2, v94, v2, vcc
	v_cmp_lt_f32_e64 vcc, |v1|, s3
	s_nop 1
	v_cndmask_b32_e32 v1, v2, v1, vcc
